# P1 epilogue: PROJ stores without the nontemporal hint (kept in L2/MALL for the attention phase)
# baseline (speedup 1.0000x reference)
.LBB0_174:
	s_xor_b64 s[56:57], s[56:57], -1
	s_andn2_b64 vcc, exec, s[56:57]
	s_mov_b64 s[56:57], -1
	s_cbranch_vccnz .LBB0_176
	s_cmp_eq_u32 s27, 0
	s_cselect_b64 vcc, -1, 0
	s_ashr_i32 s53, s52, 31
	s_lshl_b64 s[56:57], s[52:53], 1
	s_add_u32 s51, s54, s56
	s_addc_u32 s53, s55, s57
	s_lshl_b32 s56, s65, 1
	v_add_u32_e32 v148, s82, v163
	s_add_u32 s56, s51, s56
	s_addc_u32 s57, s53, 0
	s_sub_i32 s51, 11, s27
	v_and_b32_e32 v146, 0x7ff, v148
	v_lshlrev_b32_e32 v147, s51, v148
	v_lshrrev_b32_e32 v146, s27, v146
	v_and_b32_e32 v147, 0x7ff, v147
	v_and_or_b32 v146, v148, s73, v146
	v_add_u32_e32 v146, v146, v147
	v_lshlrev_b32_e32 v160, 1, v162
	v_cndmask_b32_e32 v146, v146, v148, vcc
	v_lshl_add_u64 v[128:129], s[56:57], 0, v[160:161]
	v_pk_mul_f32 v[132:133], v[122:123], v[174:175] op_sel_hi:[1,0]
	v_pk_mul_f32 v[130:131], v[120:121], v[174:175] op_sel_hi:[1,0]
	v_pk_mul_f32 v[134:135], v[126:127], v[174:175] op_sel_hi:[1,0]
	v_pk_mul_f32 v[136:137], v[124:125], v[174:175] op_sel_hi:[1,0]
	v_mad_i64_i32 v[146:147], s[56:57], s50, v146, 0
	v_pk_mul_f32 v[138:139], v[114:115], v[174:175] op_sel_hi:[1,0]
	v_pk_mul_f32 v[140:141], v[112:113], v[174:175] op_sel_hi:[1,0]
	v_pk_mul_f32 v[142:143], v[118:119], v[174:175] op_sel_hi:[1,0]
	v_pk_mul_f32 v[144:145], v[116:117], v[174:175] op_sel_hi:[1,0]
	v_lshl_add_u64 v[146:147], v[146:147], 1, v[128:129]
	v_cvt_pk_bf16_f32 v130, v130, v131
	v_cvt_pk_bf16_f32 v131, v132, v133
	v_cvt_pk_bf16_f32 v132, v136, v137
	v_cvt_pk_bf16_f32 v133, v134, v135
	global_store_dwordx4 v[146:147], v[130:133], off
	v_pk_mul_f32 v[134:135], v[106:107], v[174:175] op_sel_hi:[1,0]
	v_pk_mul_f32 v[136:137], v[104:105], v[174:175] op_sel_hi:[1,0]
	v_cvt_pk_bf16_f32 v130, v140, v141
	v_cvt_pk_bf16_f32 v131, v138, v139
	v_cvt_pk_bf16_f32 v132, v144, v145
	v_cvt_pk_bf16_f32 v133, v142, v143
	global_store_dwordx4 v[146:147], v[130:133], off offset:256
	v_add_u32_e32 v146, 16, v148
	v_and_b32_e32 v147, 0x7ff, v146
	v_lshlrev_b32_e32 v149, s51, v146
	v_lshrrev_b32_e32 v147, s27, v147
	v_and_b32_e32 v149, 0x7ff, v149
	v_and_or_b32 v147, v146, s73, v147
	v_add_u32_e32 v147, v147, v149
	v_cndmask_b32_e32 v146, v147, v146, vcc
	v_pk_mul_f32 v[132:133], v[110:111], v[174:175] op_sel_hi:[1,0]
	v_pk_mul_f32 v[130:131], v[108:109], v[174:175] op_sel_hi:[1,0]
	v_mad_i64_i32 v[146:147], s[56:57], s50, v146, 0
	v_pk_mul_f32 v[138:139], v[102:103], v[174:175] op_sel_hi:[1,0]
	v_pk_mul_f32 v[140:141], v[100:101], v[174:175] op_sel_hi:[1,0]
	v_pk_mul_f32 v[142:143], v[98:99], v[174:175] op_sel_hi:[1,0]
	v_pk_mul_f32 v[144:145], v[96:97], v[174:175] op_sel_hi:[1,0]
	v_lshl_add_u64 v[146:147], v[146:147], 1, v[128:129]
	v_cvt_pk_bf16_f32 v130, v130, v131
	v_cvt_pk_bf16_f32 v131, v132, v133
	v_cvt_pk_bf16_f32 v132, v136, v137
	v_cvt_pk_bf16_f32 v133, v134, v135
	global_store_dwordx4 v[146:147], v[130:133], off
	v_pk_mul_f32 v[134:135], v[90:91], v[174:175] op_sel_hi:[1,0]
	v_pk_mul_f32 v[136:137], v[88:89], v[174:175] op_sel_hi:[1,0]
	v_cvt_pk_bf16_f32 v130, v140, v141
	v_cvt_pk_bf16_f32 v131, v138, v139
	v_cvt_pk_bf16_f32 v132, v144, v145
	v_cvt_pk_bf16_f32 v133, v142, v143
	global_store_dwordx4 v[146:147], v[130:133], off offset:256
	v_add_u32_e32 v146, 32, v148
	v_and_b32_e32 v147, 0x7ff, v146
	v_lshlrev_b32_e32 v149, s51, v146
	v_lshrrev_b32_e32 v147, s27, v147
	v_and_b32_e32 v149, 0x7ff, v149
	v_and_or_b32 v147, v146, s73, v147
	v_add_u32_e32 v147, v147, v149
	v_cndmask_b32_e32 v146, v147, v146, vcc
	v_pk_mul_f32 v[132:133], v[94:95], v[174:175] op_sel_hi:[1,0]
	v_pk_mul_f32 v[130:131], v[92:93], v[174:175] op_sel_hi:[1,0]
	v_mad_i64_i32 v[146:147], s[56:57], s50, v146, 0
	v_pk_mul_f32 v[138:139], v[86:87], v[174:175] op_sel_hi:[1,0]
	v_pk_mul_f32 v[140:141], v[84:85], v[174:175] op_sel_hi:[1,0]
	v_pk_mul_f32 v[142:143], v[82:83], v[174:175] op_sel_hi:[1,0]
	v_pk_mul_f32 v[144:145], v[80:81], v[174:175] op_sel_hi:[1,0]
	v_lshl_add_u64 v[146:147], v[146:147], 1, v[128:129]
	v_cvt_pk_bf16_f32 v130, v130, v131
	v_cvt_pk_bf16_f32 v131, v132, v133
	v_cvt_pk_bf16_f32 v132, v136, v137
	v_cvt_pk_bf16_f32 v133, v134, v135
	global_store_dwordx4 v[146:147], v[130:133], off
	v_pk_mul_f32 v[134:135], v[74:75], v[174:175] op_sel_hi:[1,0]
	v_pk_mul_f32 v[136:137], v[72:73], v[174:175] op_sel_hi:[1,0]
	v_cvt_pk_bf16_f32 v130, v140, v141
	v_cvt_pk_bf16_f32 v131, v138, v139
	v_cvt_pk_bf16_f32 v132, v144, v145
	v_cvt_pk_bf16_f32 v133, v142, v143
	global_store_dwordx4 v[146:147], v[130:133], off offset:256
	v_add_u32_e32 v146, 48, v148
	v_and_b32_e32 v147, 0x7ff, v146
	v_lshlrev_b32_e32 v149, s51, v146
	v_lshrrev_b32_e32 v147, s27, v147
	v_and_b32_e32 v149, 0x7ff, v149
	v_and_or_b32 v147, v146, s73, v147
	v_add_u32_e32 v147, v147, v149
	v_cndmask_b32_e32 v146, v147, v146, vcc
	v_pk_mul_f32 v[132:133], v[78:79], v[174:175] op_sel_hi:[1,0]
	v_pk_mul_f32 v[130:131], v[76:77], v[174:175] op_sel_hi:[1,0]
	v_mad_i64_i32 v[146:147], s[56:57], s50, v146, 0
	v_pk_mul_f32 v[138:139], v[70:71], v[174:175] op_sel_hi:[1,0]
	v_pk_mul_f32 v[140:141], v[68:69], v[174:175] op_sel_hi:[1,0]
	v_pk_mul_f32 v[142:143], v[66:67], v[174:175] op_sel_hi:[1,0]
	v_pk_mul_f32 v[144:145], v[64:65], v[174:175] op_sel_hi:[1,0]
	v_lshl_add_u64 v[146:147], v[146:147], 1, v[128:129]
	v_cvt_pk_bf16_f32 v130, v130, v131
	v_cvt_pk_bf16_f32 v131, v132, v133
	v_cvt_pk_bf16_f32 v132, v136, v137
	v_cvt_pk_bf16_f32 v133, v134, v135
	global_store_dwordx4 v[146:147], v[130:133], off
	v_pk_mul_f32 v[134:135], v[58:59], v[174:175] op_sel_hi:[1,0]
	v_pk_mul_f32 v[136:137], v[56:57], v[174:175] op_sel_hi:[1,0]
	v_cvt_pk_bf16_f32 v130, v140, v141
	v_cvt_pk_bf16_f32 v131, v138, v139
	v_cvt_pk_bf16_f32 v132, v144, v145
	v_cvt_pk_bf16_f32 v133, v142, v143
	global_store_dwordx4 v[146:147], v[130:133], off offset:256
	v_add_u32_e32 v146, 0x80, v148
	v_and_b32_e32 v147, 0x7ff, v146
	v_lshlrev_b32_e32 v149, s51, v146
	v_lshrrev_b32_e32 v147, s27, v147
	v_and_b32_e32 v149, 0x7ff, v149
	v_and_or_b32 v147, v146, s73, v147
	v_add_u32_e32 v147, v147, v149
	v_cndmask_b32_e32 v146, v147, v146, vcc
	v_pk_mul_f32 v[132:133], v[62:63], v[174:175] op_sel_hi:[1,0]
	v_pk_mul_f32 v[130:131], v[60:61], v[174:175] op_sel_hi:[1,0]
	v_mad_i64_i32 v[146:147], s[56:57], s50, v146, 0
	v_pk_mul_f32 v[138:139], v[54:55], v[174:175] op_sel_hi:[1,0]
	v_pk_mul_f32 v[140:141], v[52:53], v[174:175] op_sel_hi:[1,0]
	v_pk_mul_f32 v[142:143], v[50:51], v[174:175] op_sel_hi:[1,0]
	v_pk_mul_f32 v[144:145], v[48:49], v[174:175] op_sel_hi:[1,0]
	v_lshl_add_u64 v[146:147], v[146:147], 1, v[128:129]
	v_cvt_pk_bf16_f32 v130, v130, v131
	v_cvt_pk_bf16_f32 v131, v132, v133
	v_cvt_pk_bf16_f32 v132, v136, v137
	v_cvt_pk_bf16_f32 v133, v134, v135
	global_store_dwordx4 v[146:147], v[130:133], off
	v_pk_mul_f32 v[134:135], v[42:43], v[174:175] op_sel_hi:[1,0]
	v_pk_mul_f32 v[136:137], v[40:41], v[174:175] op_sel_hi:[1,0]
	v_cvt_pk_bf16_f32 v130, v140, v141
	v_cvt_pk_bf16_f32 v131, v138, v139
	v_cvt_pk_bf16_f32 v132, v144, v145
	v_cvt_pk_bf16_f32 v133, v142, v143
	global_store_dwordx4 v[146:147], v[130:133], off offset:256
	v_add_u32_e32 v146, 0x90, v148
	v_and_b32_e32 v147, 0x7ff, v146
	v_lshlrev_b32_e32 v149, s51, v146
	v_lshrrev_b32_e32 v147, s27, v147
	v_and_b32_e32 v149, 0x7ff, v149
	v_and_or_b32 v147, v146, s73, v147
	v_add_u32_e32 v147, v147, v149
	v_cndmask_b32_e32 v146, v147, v146, vcc
	v_pk_mul_f32 v[132:133], v[46:47], v[174:175] op_sel_hi:[1,0]
	v_pk_mul_f32 v[130:131], v[44:45], v[174:175] op_sel_hi:[1,0]
	v_mad_i64_i32 v[146:147], s[56:57], s50, v146, 0
	v_pk_mul_f32 v[138:139], v[38:39], v[174:175] op_sel_hi:[1,0]
	v_pk_mul_f32 v[140:141], v[36:37], v[174:175] op_sel_hi:[1,0]
	v_pk_mul_f32 v[142:143], v[34:35], v[174:175] op_sel_hi:[1,0]
	v_pk_mul_f32 v[144:145], v[32:33], v[174:175] op_sel_hi:[1,0]
	v_lshl_add_u64 v[146:147], v[146:147], 1, v[128:129]
	v_cvt_pk_bf16_f32 v130, v130, v131
	v_cvt_pk_bf16_f32 v131, v132, v133
	v_cvt_pk_bf16_f32 v132, v136, v137
	v_cvt_pk_bf16_f32 v133, v134, v135
	global_store_dwordx4 v[146:147], v[130:133], off
	v_pk_mul_f32 v[134:135], v[26:27], v[174:175] op_sel_hi:[1,0]
	v_pk_mul_f32 v[136:137], v[24:25], v[174:175] op_sel_hi:[1,0]
	v_cvt_pk_bf16_f32 v130, v140, v141
	v_cvt_pk_bf16_f32 v131, v138, v139
	v_cvt_pk_bf16_f32 v132, v144, v145
	v_cvt_pk_bf16_f32 v133, v142, v143
	global_store_dwordx4 v[146:147], v[130:133], off offset:256
	v_add_u32_e32 v146, 0xa0, v148
	v_and_b32_e32 v147, 0x7ff, v146
	v_lshlrev_b32_e32 v149, s51, v146
	v_lshrrev_b32_e32 v147, s27, v147
	v_and_b32_e32 v149, 0x7ff, v149
	v_and_or_b32 v147, v146, s73, v147
	v_add_u32_e32 v147, v147, v149
	v_cndmask_b32_e32 v146, v147, v146, vcc
	v_pk_mul_f32 v[132:133], v[30:31], v[174:175] op_sel_hi:[1,0]
	v_pk_mul_f32 v[130:131], v[28:29], v[174:175] op_sel_hi:[1,0]
	v_mad_i64_i32 v[146:147], s[56:57], s50, v146, 0
	v_pk_mul_f32 v[138:139], v[22:23], v[174:175] op_sel_hi:[1,0]
	v_pk_mul_f32 v[140:141], v[20:21], v[174:175] op_sel_hi:[1,0]
	v_pk_mul_f32 v[142:143], v[18:19], v[174:175] op_sel_hi:[1,0]
	v_pk_mul_f32 v[144:145], v[16:17], v[174:175] op_sel_hi:[1,0]
	v_lshl_add_u64 v[146:147], v[146:147], 1, v[128:129]
	v_cvt_pk_bf16_f32 v130, v130, v131
	v_cvt_pk_bf16_f32 v131, v132, v133
	v_cvt_pk_bf16_f32 v132, v136, v137
	v_cvt_pk_bf16_f32 v133, v134, v135
	global_store_dwordx4 v[146:147], v[130:133], off
	v_pk_mul_f32 v[134:135], v[10:11], v[174:175] op_sel_hi:[1,0]
	v_pk_mul_f32 v[136:137], v[8:9], v[174:175] op_sel_hi:[1,0]
	v_cvt_pk_bf16_f32 v130, v140, v141
	v_cvt_pk_bf16_f32 v131, v138, v139
	v_cvt_pk_bf16_f32 v132, v144, v145
	v_cvt_pk_bf16_f32 v133, v142, v143
	global_store_dwordx4 v[146:147], v[130:133], off offset:256
	v_add_u32_e32 v146, 0xb0, v148
	v_and_b32_e32 v147, 0x7ff, v146
	v_lshlrev_b32_e32 v148, s51, v146
	v_lshrrev_b32_e32 v147, s27, v147
	v_and_b32_e32 v148, 0x7ff, v148
	v_and_or_b32 v147, v146, s73, v147
	v_add_u32_e32 v147, v147, v148
	v_cndmask_b32_e32 v146, v147, v146, vcc
	v_pk_mul_f32 v[130:131], v[14:15], v[174:175] op_sel_hi:[1,0]
	v_pk_mul_f32 v[132:133], v[12:13], v[174:175] op_sel_hi:[1,0]
	v_mad_i64_i32 v[146:147], s[56:57], s50, v146, 0
	v_pk_mul_f32 v[138:139], v[6:7], v[174:175] op_sel_hi:[1,0]
	v_pk_mul_f32 v[140:141], v[4:5], v[174:175] op_sel_hi:[1,0]
	v_pk_mul_f32 v[142:143], v[2:3], v[174:175] op_sel_hi:[1,0]
	v_pk_mul_f32 v[144:145], v[0:1], v[174:175] op_sel_hi:[1,0]
	v_lshl_add_u64 v[146:147], v[146:147], 1, v[128:129]
	v_cvt_pk_bf16_f32 v128, v132, v133
	v_cvt_pk_bf16_f32 v129, v130, v131
	v_cvt_pk_bf16_f32 v130, v136, v137
	v_cvt_pk_bf16_f32 v131, v134, v135
	global_store_dwordx4 v[146:147], v[128:131], off
	s_mov_b64 s[56:57], 0
	s_nop 0
	v_cvt_pk_bf16_f32 v128, v140, v141
	v_cvt_pk_bf16_f32 v129, v138, v139
	v_cvt_pk_bf16_f32 v130, v144, v145
	v_cvt_pk_bf16_f32 v131, v142, v143
	global_store_dwordx4 v[146:147], v[128:131], off offset:256
.LBB0_176:
	s_andn2_b64 vcc, exec, s[56:57]
	s_cbranch_vccnz .LBB0_178
	v_mul_f32_e32 v131, 0xbfb8aa3b, v120
	v_exp_f32_e32 v131, v131
	v_mul_f32_e32 v132, 0xbfb8aa3b, v121
	v_exp_f32_e32 v133, v132
	v_mul_f32_e32 v134, 0xbfb8aa3b, v123
	v_add_f32_e32 v131, 1.0, v131
	v_rcp_f32_e32 v132, v131
	v_add_f32_e32 v131, 1.0, v133
	v_rcp_f32_e32 v133, v131
	v_mul_f32_e32 v131, 0xbfb8aa3b, v122
	v_exp_f32_e32 v131, v131
	v_exp_f32_e32 v135, v134
	v_mul_f32_e32 v136, 0xbfb8aa3b, v125
	v_exp_f32_e32 v137, v136
	v_add_f32_e32 v131, 1.0, v131
	v_rcp_f32_e32 v134, v131
	v_add_f32_e32 v131, 1.0, v135
	v_rcp_f32_e32 v135, v131
	v_mul_f32_e32 v131, 0xbfb8aa3b, v124
	v_exp_f32_e32 v131, v131
	v_mul_f32_e32 v138, 0xbfb8aa3b, v127
	v_exp_f32_e32 v139, v138
	v_mul_f32_e32 v140, 0xbfb8aa3b, v113
	v_add_f32_e32 v131, 1.0, v131
	v_rcp_f32_e32 v136, v131
	v_add_f32_e32 v131, 1.0, v137
	v_rcp_f32_e32 v137, v131
	v_mul_f32_e32 v131, 0xbfb8aa3b, v126
	v_exp_f32_e32 v131, v131
	v_exp_f32_e32 v141, v140
	s_cmp_eq_u32 s27, 0
	s_cselect_b64 vcc, -1, 0
	v_add_f32_e32 v131, 1.0, v131
	v_rcp_f32_e32 v138, v131
	v_add_f32_e32 v131, 1.0, v139
	v_rcp_f32_e32 v139, v131
	v_mul_f32_e32 v131, 0xbfb8aa3b, v112
	v_exp_f32_e32 v131, v131
	s_ashr_i32 s53, s52, 31
	s_lshl_b64 s[56:57], s[52:53], 1
	s_add_u32 s51, s54, s56
	v_add_f32_e32 v131, 1.0, v131
	v_rcp_f32_e32 v140, v131
	v_add_f32_e32 v131, 1.0, v141
	v_mul_f32_e32 v141, 0xbfb8aa3b, v114
	v_exp_f32_e32 v142, v141
	v_mul_f32_e32 v141, 0xbfb8aa3b, v115
	v_exp_f32_e32 v143, v141
	v_rcp_f32_e32 v141, v131
	v_add_f32_e32 v131, 1.0, v142
	v_rcp_f32_e32 v142, v131
	v_add_f32_e32 v131, 1.0, v143
	v_mul_f32_e32 v143, 0xbfb8aa3b, v116
	v_exp_f32_e32 v144, v143
	v_mul_f32_e32 v143, 0xbfb8aa3b, v117
	v_exp_f32_e32 v145, v143
	v_rcp_f32_e32 v143, v131
	v_add_f32_e32 v131, 1.0, v144
	v_rcp_f32_e32 v144, v131
	v_add_f32_e32 v131, 1.0, v145
	v_mul_f32_e32 v145, 0xbfb8aa3b, v118
	v_exp_f32_e32 v146, v145
	v_mul_f32_e32 v145, 0xbfb8aa3b, v119
	v_exp_f32_e32 v147, v145
	s_addc_u32 s53, s55, s57
	s_lshl_b32 s56, s65, 1
	v_rcp_f32_e32 v145, v131
	v_add_f32_e32 v131, 1.0, v146
	v_add_u32_e32 v130, s82, v163
	s_add_u32 s56, s51, s56
	v_rcp_f32_e32 v146, v131
	v_add_f32_e32 v131, 1.0, v147
	s_addc_u32 s57, s53, 0
	s_sub_i32 s51, 11, s27
	v_rcp_f32_e32 v147, v131
	v_and_b32_e32 v131, 0x7ff, v130
	v_lshlrev_b32_e32 v148, s51, v130
	v_lshrrev_b32_e32 v131, s27, v131
	v_and_b32_e32 v148, 0x7ff, v148
	v_and_or_b32 v131, v130, s73, v131
	v_add_u32_e32 v131, v131, v148
	v_lshlrev_b32_e32 v160, 1, v162
	v_cndmask_b32_e32 v131, v131, v130, vcc
	v_lshl_add_u64 v[128:129], s[56:57], 0, v[160:161]
	v_pk_mul_f32 v[132:133], v[120:121], v[132:133]
	v_pk_mul_f32 v[134:135], v[122:123], v[134:135]
	v_pk_mul_f32 v[136:137], v[124:125], v[136:137]
	v_pk_mul_f32 v[138:139], v[126:127], v[138:139]
	v_mad_i64_i32 v[148:149], s[56:57], s50, v131, 0
	v_pk_mul_f32 v[140:141], v[112:113], v[140:141]
	v_pk_mul_f32 v[142:143], v[114:115], v[142:143]
	v_pk_mul_f32 v[144:145], v[116:117], v[144:145]
	v_pk_mul_f32 v[146:147], v[118:119], v[146:147]
	v_lshl_add_u64 v[148:149], v[148:149], 1, v[128:129]
	v_cvt_pk_bf16_f32 v132, v132, v133
	v_cvt_pk_bf16_f32 v133, v134, v135
	v_cvt_pk_bf16_f32 v134, v136, v137
	v_cvt_pk_bf16_f32 v135, v138, v139
	global_store_dwordx4 v[148:149], v[132:135], off
	v_mul_f32_e32 v131, 0xbfb8aa3b, v108
	v_exp_f32_e32 v131, v131
	v_cvt_pk_bf16_f32 v132, v140, v141
	v_cvt_pk_bf16_f32 v133, v142, v143
	v_cvt_pk_bf16_f32 v134, v144, v145
	v_cvt_pk_bf16_f32 v135, v146, v147
	global_store_dwordx4 v[148:149], v[132:135], off offset:256
	v_add_f32_e32 v131, 1.0, v131
	v_mul_f32_e32 v136, 0xbfb8aa3b, v105
	v_mul_f32_e32 v132, 0xbfb8aa3b, v109
	v_exp_f32_e32 v133, v132
	v_rcp_f32_e32 v132, v131
	v_mul_f32_e32 v134, 0xbfb8aa3b, v111
	v_exp_f32_e32 v135, v134
	v_add_f32_e32 v131, 1.0, v133
	v_rcp_f32_e32 v133, v131
	v_mul_f32_e32 v131, 0xbfb8aa3b, v110
	v_exp_f32_e32 v131, v131
	v_exp_f32_e32 v137, v136
	v_mul_f32_e32 v138, 0xbfb8aa3b, v107
	v_exp_f32_e32 v139, v138
	v_add_f32_e32 v131, 1.0, v131
	v_rcp_f32_e32 v134, v131
	v_add_f32_e32 v131, 1.0, v135
	v_rcp_f32_e32 v135, v131
	v_mul_f32_e32 v131, 0xbfb8aa3b, v104
	v_exp_f32_e32 v131, v131
	v_mul_f32_e32 v140, 0xbfb8aa3b, v101
	v_exp_f32_e32 v141, v140
	v_pk_mul_f32 v[132:133], v[108:109], v[132:133]
	v_add_f32_e32 v131, 1.0, v131
	v_rcp_f32_e32 v136, v131
	v_add_f32_e32 v131, 1.0, v137
	v_rcp_f32_e32 v137, v131
	v_mul_f32_e32 v131, 0xbfb8aa3b, v106
	v_exp_f32_e32 v131, v131
	v_pk_mul_f32 v[134:135], v[110:111], v[134:135]
	v_pk_mul_f32 v[136:137], v[104:105], v[136:137]
	v_cvt_pk_bf16_f32 v132, v132, v133
	v_add_f32_e32 v131, 1.0, v131
	v_rcp_f32_e32 v138, v131
	v_add_f32_e32 v131, 1.0, v139
	v_rcp_f32_e32 v139, v131
	v_mul_f32_e32 v131, 0xbfb8aa3b, v100
	v_exp_f32_e32 v131, v131
	v_cvt_pk_bf16_f32 v133, v134, v135
	v_pk_mul_f32 v[138:139], v[106:107], v[138:139]
	v_cvt_pk_bf16_f32 v134, v136, v137
	v_add_f32_e32 v131, 1.0, v131
	v_rcp_f32_e32 v140, v131
	v_add_f32_e32 v131, 1.0, v141
	v_mul_f32_e32 v141, 0xbfb8aa3b, v102
	v_exp_f32_e32 v142, v141
	v_mul_f32_e32 v141, 0xbfb8aa3b, v103
	v_exp_f32_e32 v143, v141
	v_rcp_f32_e32 v141, v131
	v_add_f32_e32 v131, 1.0, v142
	v_rcp_f32_e32 v142, v131
	v_add_f32_e32 v131, 1.0, v143
	v_mul_f32_e32 v143, 0xbfb8aa3b, v96
	v_exp_f32_e32 v144, v143
	v_mul_f32_e32 v143, 0xbfb8aa3b, v97
	v_exp_f32_e32 v145, v143
	v_rcp_f32_e32 v143, v131
	v_add_f32_e32 v131, 1.0, v144
	v_rcp_f32_e32 v144, v131
	v_add_f32_e32 v131, 1.0, v145
	v_mul_f32_e32 v145, 0xbfb8aa3b, v98
	v_exp_f32_e32 v146, v145
	v_mul_f32_e32 v145, 0xbfb8aa3b, v99
	v_exp_f32_e32 v147, v145
	v_rcp_f32_e32 v145, v131
	v_add_f32_e32 v131, 1.0, v146
	v_rcp_f32_e32 v146, v131
	v_add_f32_e32 v131, 1.0, v147
	v_rcp_f32_e32 v147, v131
	v_add_u32_e32 v131, 16, v130
	v_and_b32_e32 v148, 0x7ff, v131
	v_lshlrev_b32_e32 v149, s51, v131
	v_lshrrev_b32_e32 v148, s27, v148
	v_and_b32_e32 v149, 0x7ff, v149
	v_and_or_b32 v148, v131, s73, v148
	v_add_u32_e32 v148, v148, v149
	v_cndmask_b32_e32 v131, v148, v131, vcc
	v_mad_i64_i32 v[148:149], s[56:57], s50, v131, 0
	v_pk_mul_f32 v[140:141], v[100:101], v[140:141]
	v_pk_mul_f32 v[142:143], v[102:103], v[142:143]
	v_pk_mul_f32 v[144:145], v[96:97], v[144:145]
	v_pk_mul_f32 v[146:147], v[98:99], v[146:147]
	v_lshl_add_u64 v[148:149], v[148:149], 1, v[128:129]
	v_cvt_pk_bf16_f32 v135, v138, v139
	global_store_dwordx4 v[148:149], v[132:135], off
	v_mul_f32_e32 v131, 0xbfb8aa3b, v92
	v_exp_f32_e32 v131, v131
	v_cvt_pk_bf16_f32 v132, v140, v141
	v_cvt_pk_bf16_f32 v133, v142, v143
	v_cvt_pk_bf16_f32 v134, v144, v145
	v_cvt_pk_bf16_f32 v135, v146, v147
	global_store_dwordx4 v[148:149], v[132:135], off offset:256
	v_add_f32_e32 v131, 1.0, v131
	v_mul_f32_e32 v136, 0xbfb8aa3b, v89
	v_mul_f32_e32 v132, 0xbfb8aa3b, v93
	v_exp_f32_e32 v133, v132
	v_rcp_f32_e32 v132, v131
	v_mul_f32_e32 v134, 0xbfb8aa3b, v95
	v_exp_f32_e32 v135, v134
	v_add_f32_e32 v131, 1.0, v133
	v_rcp_f32_e32 v133, v131
	v_mul_f32_e32 v131, 0xbfb8aa3b, v94
	v_exp_f32_e32 v131, v131
	v_exp_f32_e32 v137, v136
	v_mul_f32_e32 v138, 0xbfb8aa3b, v91
	v_exp_f32_e32 v139, v138
	v_add_f32_e32 v131, 1.0, v131
	v_rcp_f32_e32 v134, v131
	v_add_f32_e32 v131, 1.0, v135
	v_rcp_f32_e32 v135, v131
	v_mul_f32_e32 v131, 0xbfb8aa3b, v88
	v_exp_f32_e32 v131, v131
	v_mul_f32_e32 v140, 0xbfb8aa3b, v85
	v_exp_f32_e32 v141, v140
	v_pk_mul_f32 v[132:133], v[92:93], v[132:133]
	v_add_f32_e32 v131, 1.0, v131
	v_rcp_f32_e32 v136, v131
	v_add_f32_e32 v131, 1.0, v137
	v_rcp_f32_e32 v137, v131
	v_mul_f32_e32 v131, 0xbfb8aa3b, v90
	v_exp_f32_e32 v131, v131
	v_pk_mul_f32 v[134:135], v[94:95], v[134:135]
	v_pk_mul_f32 v[136:137], v[88:89], v[136:137]
	v_cvt_pk_bf16_f32 v132, v132, v133
	v_add_f32_e32 v131, 1.0, v131
	v_rcp_f32_e32 v138, v131
	v_add_f32_e32 v131, 1.0, v139
	v_rcp_f32_e32 v139, v131
	v_mul_f32_e32 v131, 0xbfb8aa3b, v84
	v_exp_f32_e32 v131, v131
	v_cvt_pk_bf16_f32 v133, v134, v135
	v_pk_mul_f32 v[138:139], v[90:91], v[138:139]
	v_cvt_pk_bf16_f32 v134, v136, v137
	v_add_f32_e32 v131, 1.0, v131
	v_rcp_f32_e32 v140, v131
	v_add_f32_e32 v131, 1.0, v141
	v_mul_f32_e32 v141, 0xbfb8aa3b, v86
	v_exp_f32_e32 v142, v141
	v_mul_f32_e32 v141, 0xbfb8aa3b, v87
	v_exp_f32_e32 v143, v141
	v_rcp_f32_e32 v141, v131
	v_add_f32_e32 v131, 1.0, v142
	v_rcp_f32_e32 v142, v131
	v_add_f32_e32 v131, 1.0, v143
	v_mul_f32_e32 v143, 0xbfb8aa3b, v80
	v_exp_f32_e32 v144, v143
	v_mul_f32_e32 v143, 0xbfb8aa3b, v81
	v_exp_f32_e32 v145, v143
	v_rcp_f32_e32 v143, v131
	v_add_f32_e32 v131, 1.0, v144
	v_rcp_f32_e32 v144, v131
	v_add_f32_e32 v131, 1.0, v145
	v_mul_f32_e32 v145, 0xbfb8aa3b, v82
	v_exp_f32_e32 v146, v145
	v_mul_f32_e32 v145, 0xbfb8aa3b, v83
	v_exp_f32_e32 v147, v145
	v_rcp_f32_e32 v145, v131
	v_add_f32_e32 v131, 1.0, v146
	v_rcp_f32_e32 v146, v131
	v_add_f32_e32 v131, 1.0, v147
	v_rcp_f32_e32 v147, v131
	v_add_u32_e32 v131, 32, v130
	v_and_b32_e32 v148, 0x7ff, v131
	v_lshlrev_b32_e32 v149, s51, v131
	v_lshrrev_b32_e32 v148, s27, v148
	v_and_b32_e32 v149, 0x7ff, v149
	v_and_or_b32 v148, v131, s73, v148
	v_add_u32_e32 v148, v148, v149
	v_cndmask_b32_e32 v131, v148, v131, vcc
	v_mad_i64_i32 v[148:149], s[56:57], s50, v131, 0
	v_pk_mul_f32 v[140:141], v[84:85], v[140:141]
	v_pk_mul_f32 v[142:143], v[86:87], v[142:143]
	v_pk_mul_f32 v[144:145], v[80:81], v[144:145]
	v_pk_mul_f32 v[146:147], v[82:83], v[146:147]
	v_lshl_add_u64 v[148:149], v[148:149], 1, v[128:129]
	v_cvt_pk_bf16_f32 v135, v138, v139
	global_store_dwordx4 v[148:149], v[132:135], off
	v_mul_f32_e32 v131, 0xbfb8aa3b, v76
	v_exp_f32_e32 v131, v131
	v_cvt_pk_bf16_f32 v132, v140, v141
	v_cvt_pk_bf16_f32 v133, v142, v143
	v_cvt_pk_bf16_f32 v134, v144, v145
	v_cvt_pk_bf16_f32 v135, v146, v147
	global_store_dwordx4 v[148:149], v[132:135], off offset:256
	v_add_f32_e32 v131, 1.0, v131
	v_mul_f32_e32 v136, 0xbfb8aa3b, v73
	v_mul_f32_e32 v132, 0xbfb8aa3b, v77
	v_exp_f32_e32 v133, v132
	v_rcp_f32_e32 v132, v131
	v_mul_f32_e32 v134, 0xbfb8aa3b, v79
	v_exp_f32_e32 v135, v134
	v_add_f32_e32 v131, 1.0, v133
	v_rcp_f32_e32 v133, v131
	v_mul_f32_e32 v131, 0xbfb8aa3b, v78
	v_exp_f32_e32 v131, v131
	v_exp_f32_e32 v137, v136
	v_mul_f32_e32 v138, 0xbfb8aa3b, v75
	v_exp_f32_e32 v139, v138
	v_add_f32_e32 v131, 1.0, v131
	v_rcp_f32_e32 v134, v131
	v_add_f32_e32 v131, 1.0, v135
	v_rcp_f32_e32 v135, v131
	v_mul_f32_e32 v131, 0xbfb8aa3b, v72
	v_exp_f32_e32 v131, v131
	v_mul_f32_e32 v140, 0xbfb8aa3b, v69
	v_exp_f32_e32 v141, v140
	v_pk_mul_f32 v[132:133], v[76:77], v[132:133]
	v_add_f32_e32 v131, 1.0, v131
	v_rcp_f32_e32 v136, v131
	v_add_f32_e32 v131, 1.0, v137
	v_rcp_f32_e32 v137, v131
	v_mul_f32_e32 v131, 0xbfb8aa3b, v74
	v_exp_f32_e32 v131, v131
	v_pk_mul_f32 v[134:135], v[78:79], v[134:135]
	v_pk_mul_f32 v[136:137], v[72:73], v[136:137]
	v_cvt_pk_bf16_f32 v132, v132, v133
	v_add_f32_e32 v131, 1.0, v131
	v_rcp_f32_e32 v138, v131
	v_add_f32_e32 v131, 1.0, v139
	v_rcp_f32_e32 v139, v131
	v_mul_f32_e32 v131, 0xbfb8aa3b, v68
	v_exp_f32_e32 v131, v131
	v_cvt_pk_bf16_f32 v133, v134, v135
	v_pk_mul_f32 v[138:139], v[74:75], v[138:139]
	v_cvt_pk_bf16_f32 v134, v136, v137
	v_add_f32_e32 v131, 1.0, v131
	v_rcp_f32_e32 v140, v131
	v_add_f32_e32 v131, 1.0, v141
	v_mul_f32_e32 v141, 0xbfb8aa3b, v70
	v_exp_f32_e32 v142, v141
	v_mul_f32_e32 v141, 0xbfb8aa3b, v71
	v_exp_f32_e32 v143, v141
	v_rcp_f32_e32 v141, v131
	v_add_f32_e32 v131, 1.0, v142
	v_rcp_f32_e32 v142, v131
	v_add_f32_e32 v131, 1.0, v143
	v_mul_f32_e32 v143, 0xbfb8aa3b, v64
	v_exp_f32_e32 v144, v143
	v_mul_f32_e32 v143, 0xbfb8aa3b, v65
	v_exp_f32_e32 v145, v143
	v_rcp_f32_e32 v143, v131
	v_add_f32_e32 v131, 1.0, v144
	v_rcp_f32_e32 v144, v131
	v_add_f32_e32 v131, 1.0, v145
	v_mul_f32_e32 v145, 0xbfb8aa3b, v66
	v_exp_f32_e32 v146, v145
	v_mul_f32_e32 v145, 0xbfb8aa3b, v67
	v_exp_f32_e32 v147, v145
	v_rcp_f32_e32 v145, v131
	v_add_f32_e32 v131, 1.0, v146
	v_rcp_f32_e32 v146, v131
	v_add_f32_e32 v131, 1.0, v147
	v_rcp_f32_e32 v147, v131
	v_add_u32_e32 v131, 48, v130
	v_and_b32_e32 v148, 0x7ff, v131
	v_lshlrev_b32_e32 v149, s51, v131
	v_lshrrev_b32_e32 v148, s27, v148
	v_and_b32_e32 v149, 0x7ff, v149
	v_and_or_b32 v148, v131, s73, v148
	v_add_u32_e32 v148, v148, v149
	v_cndmask_b32_e32 v131, v148, v131, vcc
	v_mad_i64_i32 v[148:149], s[56:57], s50, v131, 0
	v_pk_mul_f32 v[140:141], v[68:69], v[140:141]
	v_pk_mul_f32 v[142:143], v[70:71], v[142:143]
	v_pk_mul_f32 v[144:145], v[64:65], v[144:145]
	v_pk_mul_f32 v[146:147], v[66:67], v[146:147]
	v_lshl_add_u64 v[148:149], v[148:149], 1, v[128:129]
	v_cvt_pk_bf16_f32 v135, v138, v139
	global_store_dwordx4 v[148:149], v[132:135], off
	v_mul_f32_e32 v131, 0xbfb8aa3b, v60
	v_exp_f32_e32 v131, v131
	v_cvt_pk_bf16_f32 v132, v140, v141
	v_cvt_pk_bf16_f32 v133, v142, v143
	v_cvt_pk_bf16_f32 v134, v144, v145
	v_cvt_pk_bf16_f32 v135, v146, v147
	global_store_dwordx4 v[148:149], v[132:135], off offset:256
	v_add_f32_e32 v131, 1.0, v131
	v_mul_f32_e32 v136, 0xbfb8aa3b, v57
	v_mul_f32_e32 v132, 0xbfb8aa3b, v61
	v_exp_f32_e32 v133, v132
	v_rcp_f32_e32 v132, v131
	v_mul_f32_e32 v134, 0xbfb8aa3b, v63
	v_exp_f32_e32 v135, v134
	v_add_f32_e32 v131, 1.0, v133
	v_rcp_f32_e32 v133, v131
	v_mul_f32_e32 v131, 0xbfb8aa3b, v62
	v_exp_f32_e32 v131, v131
	v_exp_f32_e32 v137, v136
	v_mul_f32_e32 v138, 0xbfb8aa3b, v59
	v_exp_f32_e32 v139, v138
	v_add_f32_e32 v131, 1.0, v131
	v_rcp_f32_e32 v134, v131
	v_add_f32_e32 v131, 1.0, v135
	v_rcp_f32_e32 v135, v131
	v_mul_f32_e32 v131, 0xbfb8aa3b, v56
	v_exp_f32_e32 v131, v131
	v_mul_f32_e32 v140, 0xbfb8aa3b, v53
	v_exp_f32_e32 v141, v140
	v_add_u32_e32 v148, 0x80, v130
	v_add_f32_e32 v131, 1.0, v131
	v_rcp_f32_e32 v136, v131
	v_add_f32_e32 v131, 1.0, v137
	v_rcp_f32_e32 v137, v131
	v_mul_f32_e32 v131, 0xbfb8aa3b, v58
	v_exp_f32_e32 v131, v131
	v_lshlrev_b32_e32 v149, s51, v148
	v_and_b32_e32 v149, 0x7ff, v149
	v_pk_mul_f32 v[132:133], v[60:61], v[132:133]
	v_add_f32_e32 v131, 1.0, v131
	v_rcp_f32_e32 v138, v131
	v_add_f32_e32 v131, 1.0, v139
	v_rcp_f32_e32 v139, v131
	v_mul_f32_e32 v131, 0xbfb8aa3b, v52
	v_exp_f32_e32 v131, v131
	v_pk_mul_f32 v[134:135], v[62:63], v[134:135]
	v_pk_mul_f32 v[136:137], v[56:57], v[136:137]
	v_pk_mul_f32 v[138:139], v[58:59], v[138:139]
	v_add_f32_e32 v131, 1.0, v131
	v_rcp_f32_e32 v140, v131
	v_add_f32_e32 v131, 1.0, v141
	v_mul_f32_e32 v141, 0xbfb8aa3b, v54
	v_exp_f32_e32 v142, v141
	v_mul_f32_e32 v141, 0xbfb8aa3b, v55
	v_exp_f32_e32 v143, v141
	v_rcp_f32_e32 v141, v131
	v_add_f32_e32 v131, 1.0, v142
	v_rcp_f32_e32 v142, v131
	v_add_f32_e32 v131, 1.0, v143
	v_mul_f32_e32 v143, 0xbfb8aa3b, v48
	v_exp_f32_e32 v144, v143
	v_mul_f32_e32 v143, 0xbfb8aa3b, v49
	v_exp_f32_e32 v145, v143
	v_rcp_f32_e32 v143, v131
	v_add_f32_e32 v131, 1.0, v144
	v_rcp_f32_e32 v144, v131
	v_add_f32_e32 v131, 1.0, v145
	v_mul_f32_e32 v145, 0xbfb8aa3b, v50
	v_exp_f32_e32 v146, v145
	v_mul_f32_e32 v145, 0xbfb8aa3b, v51
	v_exp_f32_e32 v147, v145
	v_rcp_f32_e32 v145, v131
	v_add_f32_e32 v131, 1.0, v146
	v_rcp_f32_e32 v146, v131
	v_add_f32_e32 v131, 1.0, v147
	v_rcp_f32_e32 v147, v131
	v_and_b32_e32 v131, 0x7ff, v148
	v_lshrrev_b32_e32 v131, s27, v131
	v_and_or_b32 v131, v148, s73, v131
	v_add_u32_e32 v131, v131, v149
	v_cndmask_b32_e32 v131, v131, v148, vcc
	v_mad_i64_i32 v[148:149], s[56:57], s50, v131, 0
	v_pk_mul_f32 v[140:141], v[52:53], v[140:141]
	v_pk_mul_f32 v[142:143], v[54:55], v[142:143]
	v_pk_mul_f32 v[144:145], v[48:49], v[144:145]
	v_pk_mul_f32 v[146:147], v[50:51], v[146:147]
	v_lshl_add_u64 v[148:149], v[148:149], 1, v[128:129]
	v_cvt_pk_bf16_f32 v132, v132, v133
	v_cvt_pk_bf16_f32 v133, v134, v135
	v_cvt_pk_bf16_f32 v134, v136, v137
	v_cvt_pk_bf16_f32 v135, v138, v139
	global_store_dwordx4 v[148:149], v[132:135], off
	v_mul_f32_e32 v131, 0xbfb8aa3b, v44
	v_exp_f32_e32 v131, v131
	v_cvt_pk_bf16_f32 v132, v140, v141
	v_cvt_pk_bf16_f32 v133, v142, v143
	v_cvt_pk_bf16_f32 v134, v144, v145
	v_cvt_pk_bf16_f32 v135, v146, v147
	global_store_dwordx4 v[148:149], v[132:135], off offset:256
	v_add_f32_e32 v131, 1.0, v131
	v_mul_f32_e32 v136, 0xbfb8aa3b, v41
	v_mul_f32_e32 v132, 0xbfb8aa3b, v45
	v_exp_f32_e32 v133, v132
	v_rcp_f32_e32 v132, v131
	v_mul_f32_e32 v134, 0xbfb8aa3b, v47
	v_exp_f32_e32 v135, v134
	v_add_f32_e32 v131, 1.0, v133
	v_rcp_f32_e32 v133, v131
	v_mul_f32_e32 v131, 0xbfb8aa3b, v46
	v_exp_f32_e32 v131, v131
	v_exp_f32_e32 v137, v136
	v_mul_f32_e32 v138, 0xbfb8aa3b, v43
	v_exp_f32_e32 v139, v138
	v_add_f32_e32 v131, 1.0, v131
	v_rcp_f32_e32 v134, v131
	v_add_f32_e32 v131, 1.0, v135
	v_rcp_f32_e32 v135, v131
	v_mul_f32_e32 v131, 0xbfb8aa3b, v40
	v_exp_f32_e32 v131, v131
	v_mul_f32_e32 v140, 0xbfb8aa3b, v37
	v_exp_f32_e32 v141, v140
	v_pk_mul_f32 v[132:133], v[44:45], v[132:133]
	v_add_f32_e32 v131, 1.0, v131
	v_rcp_f32_e32 v136, v131
	v_add_f32_e32 v131, 1.0, v137
	v_rcp_f32_e32 v137, v131
	v_mul_f32_e32 v131, 0xbfb8aa3b, v42
	v_exp_f32_e32 v131, v131
	v_pk_mul_f32 v[134:135], v[46:47], v[134:135]
	v_pk_mul_f32 v[136:137], v[40:41], v[136:137]
	v_cvt_pk_bf16_f32 v132, v132, v133
	v_add_f32_e32 v131, 1.0, v131
	v_rcp_f32_e32 v138, v131
	v_add_f32_e32 v131, 1.0, v139
	v_rcp_f32_e32 v139, v131
	v_mul_f32_e32 v131, 0xbfb8aa3b, v36
	v_exp_f32_e32 v131, v131
	v_cvt_pk_bf16_f32 v133, v134, v135
	v_pk_mul_f32 v[138:139], v[42:43], v[138:139]
	v_cvt_pk_bf16_f32 v134, v136, v137
	v_add_f32_e32 v131, 1.0, v131
	v_rcp_f32_e32 v140, v131
	v_add_f32_e32 v131, 1.0, v141
	v_mul_f32_e32 v141, 0xbfb8aa3b, v38
	v_exp_f32_e32 v142, v141
	v_mul_f32_e32 v141, 0xbfb8aa3b, v39
	v_exp_f32_e32 v143, v141
	v_rcp_f32_e32 v141, v131
	v_add_f32_e32 v131, 1.0, v142
	v_rcp_f32_e32 v142, v131
	v_add_f32_e32 v131, 1.0, v143
	v_mul_f32_e32 v143, 0xbfb8aa3b, v32
	v_exp_f32_e32 v144, v143
	v_mul_f32_e32 v143, 0xbfb8aa3b, v33
	v_exp_f32_e32 v145, v143
	v_rcp_f32_e32 v143, v131
	v_add_f32_e32 v131, 1.0, v144
	v_rcp_f32_e32 v144, v131
	v_add_f32_e32 v131, 1.0, v145
	v_mul_f32_e32 v145, 0xbfb8aa3b, v34
	v_exp_f32_e32 v146, v145
	v_mul_f32_e32 v145, 0xbfb8aa3b, v35
	v_exp_f32_e32 v147, v145
	v_rcp_f32_e32 v145, v131
	v_add_f32_e32 v131, 1.0, v146
	v_rcp_f32_e32 v146, v131
	v_add_f32_e32 v131, 1.0, v147
	v_rcp_f32_e32 v147, v131
	v_add_u32_e32 v131, 0x90, v130
	v_and_b32_e32 v148, 0x7ff, v131
	v_lshlrev_b32_e32 v149, s51, v131
	v_lshrrev_b32_e32 v148, s27, v148
	v_and_b32_e32 v149, 0x7ff, v149
	v_and_or_b32 v148, v131, s73, v148
	v_add_u32_e32 v148, v148, v149
	v_cndmask_b32_e32 v131, v148, v131, vcc
	v_mad_i64_i32 v[148:149], s[56:57], s50, v131, 0
	v_pk_mul_f32 v[140:141], v[36:37], v[140:141]
	v_pk_mul_f32 v[142:143], v[38:39], v[142:143]
	v_pk_mul_f32 v[144:145], v[32:33], v[144:145]
	v_pk_mul_f32 v[146:147], v[34:35], v[146:147]
	v_lshl_add_u64 v[148:149], v[148:149], 1, v[128:129]
	v_cvt_pk_bf16_f32 v135, v138, v139
	global_store_dwordx4 v[148:149], v[132:135], off
	v_mul_f32_e32 v131, 0xbfb8aa3b, v28
	v_exp_f32_e32 v131, v131
	v_cvt_pk_bf16_f32 v132, v140, v141
	v_cvt_pk_bf16_f32 v133, v142, v143
	v_cvt_pk_bf16_f32 v134, v144, v145
	v_cvt_pk_bf16_f32 v135, v146, v147
	global_store_dwordx4 v[148:149], v[132:135], off offset:256
	v_add_f32_e32 v131, 1.0, v131
	v_mul_f32_e32 v136, 0xbfb8aa3b, v25
	v_mul_f32_e32 v132, 0xbfb8aa3b, v29
	v_exp_f32_e32 v133, v132
	v_rcp_f32_e32 v132, v131
	v_mul_f32_e32 v134, 0xbfb8aa3b, v31
	v_exp_f32_e32 v135, v134
	v_add_f32_e32 v131, 1.0, v133
	v_rcp_f32_e32 v133, v131
	v_mul_f32_e32 v131, 0xbfb8aa3b, v30
	v_exp_f32_e32 v131, v131
	v_exp_f32_e32 v137, v136
	v_mul_f32_e32 v138, 0xbfb8aa3b, v27
	v_exp_f32_e32 v139, v138
	v_add_f32_e32 v131, 1.0, v131
	v_rcp_f32_e32 v134, v131
	v_add_f32_e32 v131, 1.0, v135
	v_rcp_f32_e32 v135, v131
	v_mul_f32_e32 v131, 0xbfb8aa3b, v24
	v_exp_f32_e32 v131, v131
	v_mul_f32_e32 v140, 0xbfb8aa3b, v21
	v_exp_f32_e32 v141, v140
	v_pk_mul_f32 v[132:133], v[28:29], v[132:133]
	v_add_f32_e32 v131, 1.0, v131
	v_rcp_f32_e32 v136, v131
	v_add_f32_e32 v131, 1.0, v137
	v_rcp_f32_e32 v137, v131
	v_mul_f32_e32 v131, 0xbfb8aa3b, v26
	v_exp_f32_e32 v131, v131
	v_pk_mul_f32 v[134:135], v[30:31], v[134:135]
	v_pk_mul_f32 v[136:137], v[24:25], v[136:137]
	v_cvt_pk_bf16_f32 v132, v132, v133
	v_add_f32_e32 v131, 1.0, v131
	v_rcp_f32_e32 v138, v131
	v_add_f32_e32 v131, 1.0, v139
	v_rcp_f32_e32 v139, v131
	v_mul_f32_e32 v131, 0xbfb8aa3b, v20
	v_exp_f32_e32 v131, v131
	v_cvt_pk_bf16_f32 v133, v134, v135
	v_pk_mul_f32 v[138:139], v[26:27], v[138:139]
	v_cvt_pk_bf16_f32 v134, v136, v137
	v_add_f32_e32 v131, 1.0, v131
	v_rcp_f32_e32 v140, v131
	v_add_f32_e32 v131, 1.0, v141
	v_mul_f32_e32 v141, 0xbfb8aa3b, v22
	v_exp_f32_e32 v142, v141
	v_mul_f32_e32 v141, 0xbfb8aa3b, v23
	v_exp_f32_e32 v143, v141
	v_rcp_f32_e32 v141, v131
	v_add_f32_e32 v131, 1.0, v142
	v_rcp_f32_e32 v142, v131
	v_add_f32_e32 v131, 1.0, v143
	v_mul_f32_e32 v143, 0xbfb8aa3b, v16
	v_exp_f32_e32 v144, v143
	v_mul_f32_e32 v143, 0xbfb8aa3b, v17
	v_exp_f32_e32 v145, v143
	v_rcp_f32_e32 v143, v131
	v_add_f32_e32 v131, 1.0, v144
	v_rcp_f32_e32 v144, v131
	v_add_f32_e32 v131, 1.0, v145
	v_mul_f32_e32 v145, 0xbfb8aa3b, v18
	v_exp_f32_e32 v146, v145
	v_mul_f32_e32 v145, 0xbfb8aa3b, v19
	v_exp_f32_e32 v147, v145
	v_rcp_f32_e32 v145, v131
	v_add_f32_e32 v131, 1.0, v146
	v_rcp_f32_e32 v146, v131
	v_add_f32_e32 v131, 1.0, v147
	v_rcp_f32_e32 v147, v131
	v_add_u32_e32 v131, 0xa0, v130
	v_and_b32_e32 v148, 0x7ff, v131
	v_lshlrev_b32_e32 v149, s51, v131
	v_lshrrev_b32_e32 v148, s27, v148
	v_and_b32_e32 v149, 0x7ff, v149
	v_and_or_b32 v148, v131, s73, v148
	v_add_u32_e32 v148, v148, v149
	v_cndmask_b32_e32 v131, v148, v131, vcc
	v_mad_i64_i32 v[148:149], s[56:57], s50, v131, 0
	v_pk_mul_f32 v[140:141], v[20:21], v[140:141]
	v_pk_mul_f32 v[142:143], v[22:23], v[142:143]
	v_pk_mul_f32 v[144:145], v[16:17], v[144:145]
	v_pk_mul_f32 v[146:147], v[18:19], v[146:147]
	v_lshl_add_u64 v[148:149], v[148:149], 1, v[128:129]
	v_cvt_pk_bf16_f32 v135, v138, v139
	global_store_dwordx4 v[148:149], v[132:135], off
	v_mul_f32_e32 v131, 0xbfb8aa3b, v12
	v_exp_f32_e32 v131, v131
	v_cvt_pk_bf16_f32 v132, v140, v141
	v_cvt_pk_bf16_f32 v133, v142, v143
	v_cvt_pk_bf16_f32 v134, v144, v145
	v_cvt_pk_bf16_f32 v135, v146, v147
	global_store_dwordx4 v[148:149], v[132:135], off offset:256
	v_add_f32_e32 v131, 1.0, v131
	v_mul_f32_e32 v136, 0xbfb8aa3b, v9
	v_mul_f32_e32 v132, 0xbfb8aa3b, v13
	v_exp_f32_e32 v133, v132
	v_rcp_f32_e32 v132, v131
	v_mul_f32_e32 v134, 0xbfb8aa3b, v15
	v_exp_f32_e32 v135, v134
	v_add_f32_e32 v131, 1.0, v133
	v_rcp_f32_e32 v133, v131
	v_mul_f32_e32 v131, 0xbfb8aa3b, v14
	v_exp_f32_e32 v131, v131
	v_exp_f32_e32 v137, v136
	v_mul_f32_e32 v138, 0xbfb8aa3b, v11
	v_exp_f32_e32 v139, v138
	v_add_f32_e32 v131, 1.0, v131
	v_rcp_f32_e32 v134, v131
	v_add_f32_e32 v131, 1.0, v135
	v_rcp_f32_e32 v135, v131
	v_mul_f32_e32 v131, 0xbfb8aa3b, v8
	v_exp_f32_e32 v131, v131
	v_mul_f32_e32 v140, 0xbfb8aa3b, v5
	v_exp_f32_e32 v141, v140
	v_add_u32_e32 v130, 0xb0, v130
	v_add_f32_e32 v131, 1.0, v131
	v_rcp_f32_e32 v136, v131
	v_add_f32_e32 v131, 1.0, v137
	v_rcp_f32_e32 v137, v131
	v_mul_f32_e32 v131, 0xbfb8aa3b, v10
	v_exp_f32_e32 v131, v131
	v_lshlrev_b32_e32 v148, s51, v130
	v_and_b32_e32 v148, 0x7ff, v148
	v_pk_mul_f32 v[132:133], v[12:13], v[132:133]
	v_add_f32_e32 v131, 1.0, v131
	v_rcp_f32_e32 v138, v131
	v_add_f32_e32 v131, 1.0, v139
	v_rcp_f32_e32 v139, v131
	v_mul_f32_e32 v131, 0xbfb8aa3b, v4
	v_exp_f32_e32 v131, v131
	v_pk_mul_f32 v[134:135], v[14:15], v[134:135]
	v_pk_mul_f32 v[136:137], v[8:9], v[136:137]
	v_pk_mul_f32 v[138:139], v[10:11], v[138:139]
	v_add_f32_e32 v131, 1.0, v131
	v_rcp_f32_e32 v140, v131
	v_add_f32_e32 v131, 1.0, v141
	v_mul_f32_e32 v141, 0xbfb8aa3b, v6
	v_exp_f32_e32 v142, v141
	v_mul_f32_e32 v141, 0xbfb8aa3b, v7
	v_exp_f32_e32 v143, v141
	v_rcp_f32_e32 v141, v131
	v_add_f32_e32 v131, 1.0, v142
	v_rcp_f32_e32 v142, v131
	v_add_f32_e32 v131, 1.0, v143
	v_mul_f32_e32 v143, 0xbfb8aa3b, v0
	v_exp_f32_e32 v144, v143
	v_mul_f32_e32 v143, 0xbfb8aa3b, v1
	v_exp_f32_e32 v145, v143
	v_rcp_f32_e32 v143, v131
	v_add_f32_e32 v131, 1.0, v144
	v_rcp_f32_e32 v144, v131
	v_add_f32_e32 v131, 1.0, v145
	v_mul_f32_e32 v145, 0xbfb8aa3b, v2
	v_exp_f32_e32 v146, v145
	v_mul_f32_e32 v145, 0xbfb8aa3b, v3
	v_exp_f32_e32 v147, v145
	v_rcp_f32_e32 v145, v131
	v_add_f32_e32 v131, 1.0, v146
	v_rcp_f32_e32 v146, v131
	v_add_f32_e32 v131, 1.0, v147
	v_rcp_f32_e32 v147, v131
	v_and_b32_e32 v131, 0x7ff, v130
	v_lshrrev_b32_e32 v131, s27, v131
	v_and_or_b32 v131, v130, s73, v131
	v_add_u32_e32 v131, v131, v148
	v_cndmask_b32_e32 v130, v131, v130, vcc
	v_mad_i64_i32 v[130:131], s[56:57], s50, v130, 0
	v_pk_mul_f32 v[140:141], v[4:5], v[140:141]
	v_pk_mul_f32 v[142:143], v[6:7], v[142:143]
	v_pk_mul_f32 v[144:145], v[0:1], v[144:145]
	v_pk_mul_f32 v[146:147], v[2:3], v[146:147]
	v_lshl_add_u64 v[148:149], v[130:131], 1, v[128:129]
	v_cvt_pk_bf16_f32 v128, v132, v133
	v_cvt_pk_bf16_f32 v129, v134, v135
	v_cvt_pk_bf16_f32 v130, v136, v137
	v_cvt_pk_bf16_f32 v131, v138, v139
	global_store_dwordx4 v[148:149], v[128:131], off
	s_nop 1
	v_cvt_pk_bf16_f32 v128, v140, v141
	v_cvt_pk_bf16_f32 v129, v142, v143
	v_cvt_pk_bf16_f32 v130, v144, v145
	v_cvt_pk_bf16_f32 v131, v146, v147
	global_store_dwordx4 v[148:149], v[128:131], off offset:256

.LBB0_179:
	s_andn2_b64 vcc, exec, s[58:59]
	s_cbranch_vccnz .LBB0_190
	v_add_u32_e32 v193, s82, v163
	global_load_dwordx4 v[128:131], v[166:167], off
	global_load_dwordx4 v[132:135], v[166:167], off offset:16
	v_lshlrev_b32_e32 v136, 9, v193
	v_and_b32_e32 v160, 0xffe00, v136
	v_lshl_add_u64 v[140:141], v[164:165], 0, v[160:161]
	global_load_dwordx4 v[136:139], v[140:141], off offset:16
	s_nop 0
	global_load_dwordx4 v[140:143], v[140:141], off
	s_nop 0
	global_load_dwordx4 v[144:147], v[168:169], off
	global_load_dwordx4 v[148:151], v[168:169], off offset:16
	s_cmp_eq_u32 s27, 0
	s_cselect_b64 vcc, -1, 0
	s_ashr_i32 s53, s52, 31
	s_lshl_b64 s[52:53], s[52:53], 1
	s_add_u32 s51, s54, s52
	s_addc_u32 s53, s55, s53
	s_lshl_b32 s52, s65, 1
	v_and_b32_e32 v160, 0x7ff, v193
	s_add_u32 s52, s51, s52
	v_lshrrev_b32_e32 v176, s27, v160
	v_lshlrev_b32_e32 v160, 1, v162
	s_addc_u32 s53, s53, 0
	s_sub_i32 s51, 11, s27
	v_and_or_b32 v178, v193, s73, v176
	v_lshl_add_u64 v[176:177], s[52:53], 0, v[160:161]
	v_lshlrev_b32_e32 v160, s51, v193
	v_and_b32_e32 v160, 0x7ff, v160
	v_add_u32_e32 v160, v178, v160
	v_cndmask_b32_e32 v160, v160, v193, vcc
	v_mad_i64_i32 v[178:179], s[52:53], s50, v160, 0
	v_lshl_add_u64 v[202:203], v[178:179], 1, v[176:177]
	s_waitcnt vmcnt(0)
	v_mov_b32_e32 v178, v129
	v_mov_b32_e32 v180, v133
	v_mov_b32_e32 v181, v135
	v_mov_b32_e32 v182, v137
	v_mov_b32_e32 v183, v139
	v_mov_b32_e32 v137, v138
	v_mov_b32_e32 v179, v131
	v_mov_b32_e32 v133, v134
	v_mov_b32_e32 v129, v130
	v_mov_b32_e32 v184, v141
	v_mov_b32_e32 v185, v143
	v_mov_b32_e32 v141, v142
	v_pk_mul_f32 v[130:131], v[126:127], v[182:183]
	v_pk_mul_f32 v[196:197], v[182:183], v[180:181]
	v_pk_mul_f32 v[198:199], v[136:137], v[180:181]
	v_pk_mul_f32 v[134:135], v[124:125], v[184:185]
	v_pk_mul_f32 v[124:125], v[124:125], v[140:141]
	v_pk_mul_f32 v[194:195], v[184:185], v[178:179]
	v_pk_mul_f32 v[200:201], v[140:141], v[178:179]
	v_pk_fma_f32 v[130:131], v[122:123], v[136:137], v[130:131] neg_lo:[0,0,1] neg_hi:[0,0,1]
	v_pk_fma_f32 v[208:209], v[136:137], v[132:133], v[196:197] neg_lo:[0,0,1] neg_hi:[0,0,1]
	v_pk_fma_f32 v[214:215], v[182:183], v[132:133], v[198:199]
	v_pk_mul_f32 v[126:127], v[126:127], v[136:137]
	v_pk_fma_f32 v[134:135], v[120:121], v[140:141], v[134:135] neg_lo:[0,0,1] neg_hi:[0,0,1]
	v_pk_fma_f32 v[204:205], v[120:121], v[184:185], v[124:125]
	v_pk_fma_f32 v[210:211], v[140:141], v[128:129], v[194:195] neg_lo:[0,0,1] neg_hi:[0,0,1]
	v_pk_fma_f32 v[212:213], v[184:185], v[128:129], v[200:201]
	v_pk_mul_f32 v[124:125], v[174:175], v[130:131] op_sel_hi:[0,1]
	v_pk_mul_f32 v[130:131], v[106:107], v[214:215]
	v_pk_mul_f32 v[106:107], v[106:107], v[208:209]
	v_pk_fma_f32 v[120:121], v[122:123], v[182:183], v[126:127]
	v_pk_mul_f32 v[126:127], v[174:175], v[134:135] op_sel_hi:[0,1]
	v_pk_mul_f32 v[134:135], v[104:105], v[212:213]
	v_pk_mul_f32 v[104:105], v[104:105], v[210:211]
	v_pk_fma_f32 v[106:107], v[110:111], v[214:215], v[106:107]
	v_pk_fma_f32 v[134:135], v[108:109], v[210:211], v[134:135] neg_lo:[0,0,1] neg_hi:[0,0,1]
	v_pk_fma_f32 v[104:105], v[108:109], v[212:213], v[104:105]
	v_pk_mul_f32 v[108:109], v[174:175], v[106:107] op_sel_hi:[0,1]
	v_pk_mul_f32 v[106:107], v[96:97], v[212:213]
	v_pk_mul_f32 v[96:97], v[96:97], v[210:211]
	v_pk_fma_f32 v[130:131], v[110:111], v[208:209], v[130:131] neg_lo:[0,0,1] neg_hi:[0,0,1]
	v_pk_mul_f32 v[110:111], v[174:175], v[104:105] op_sel_hi:[0,1]
	v_pk_mul_f32 v[104:105], v[98:99], v[214:215]
	v_pk_fma_f32 v[106:107], v[100:101], v[210:211], v[106:107] neg_lo:[0,0,1] neg_hi:[0,0,1]
	v_pk_mul_f32 v[98:99], v[98:99], v[208:209]
	v_pk_fma_f32 v[100:101], v[100:101], v[212:213], v[96:97]
	v_pk_fma_f32 v[96:97], v[102:103], v[214:215], v[98:99]
	v_pk_mul_f32 v[98:99], v[174:175], v[100:101] op_sel_hi:[0,1]
	v_add_u32_e32 v100, 16, v193
	v_and_b32_e32 v101, 0x7ff, v100
	v_pk_fma_f32 v[104:105], v[102:103], v[208:209], v[104:105] neg_lo:[0,0,1] neg_hi:[0,0,1]
	v_lshlrev_b32_e32 v102, s51, v100
	v_lshrrev_b32_e32 v101, s27, v101
	v_and_b32_e32 v102, 0x7ff, v102
	v_and_or_b32 v101, v100, s73, v101
	v_add_u32_e32 v101, v101, v102
	v_pk_mul_f32 v[138:139], v[118:119], v[182:183]
	v_pk_mul_f32 v[142:143], v[116:117], v[184:185]
	v_pk_mul_f32 v[118:119], v[118:119], v[136:137]
	v_pk_mul_f32 v[116:117], v[116:117], v[140:141]
	v_cndmask_b32_e32 v100, v101, v100, vcc
	v_pk_fma_f32 v[142:143], v[112:113], v[140:141], v[142:143] neg_lo:[0,0,1] neg_hi:[0,0,1]
	v_pk_fma_f32 v[138:139], v[114:115], v[136:137], v[138:139] neg_lo:[0,0,1] neg_hi:[0,0,1]
	v_pk_fma_f32 v[206:207], v[112:113], v[184:185], v[116:117]
	v_pk_fma_f32 v[112:113], v[114:115], v[182:183], v[118:119]
	v_pk_mul_f32 v[120:121], v[174:175], v[120:121] op_sel_hi:[0,1]
	v_pk_mul_f32 v[122:123], v[174:175], v[204:205] op_sel_hi:[0,1]
	v_pk_mul_f32 v[130:131], v[174:175], v[130:131] op_sel_hi:[0,1]
	v_pk_mul_f32 v[134:135], v[174:175], v[134:135] op_sel_hi:[0,1]
	v_mad_i64_i32 v[100:101], s[52:53], s50, v100, 0
	v_pk_mul_f32 v[116:117], v[174:175], v[138:139] op_sel_hi:[0,1]
	v_pk_mul_f32 v[118:119], v[174:175], v[142:143] op_sel_hi:[0,1]
	v_pk_mul_f32 v[112:113], v[174:175], v[112:113] op_sel_hi:[0,1]
	v_pk_mul_f32 v[114:115], v[174:175], v[206:207] op_sel_hi:[0,1]
	v_cvt_pk_bf16_f32 v194, v126, v127
	v_cvt_pk_bf16_f32 v195, v124, v125
	v_cvt_pk_bf16_f32 v196, v122, v123
	v_cvt_pk_bf16_f32 v197, v120, v121
	v_pk_mul_f32 v[104:105], v[174:175], v[104:105] op_sel_hi:[0,1]
	v_pk_mul_f32 v[106:107], v[174:175], v[106:107] op_sel_hi:[0,1]
	v_pk_mul_f32 v[96:97], v[174:175], v[96:97] op_sel_hi:[0,1]
	v_lshl_add_u64 v[138:139], v[100:101], 1, v[176:177]
	v_cvt_pk_bf16_f32 v100, v134, v135
	v_cvt_pk_bf16_f32 v101, v130, v131
	v_cvt_pk_bf16_f32 v102, v110, v111
	v_cvt_pk_bf16_f32 v103, v108, v109
	v_cvt_pk_bf16_f32 v198, v118, v119
	v_cvt_pk_bf16_f32 v199, v116, v117
	v_cvt_pk_bf16_f32 v200, v114, v115
	v_cvt_pk_bf16_f32 v201, v112, v113
	global_store_dwordx4 v[202:203], v[194:197], off
	global_store_dwordx4 v[202:203], v[198:201], off offset:256
	global_store_dwordx4 v[138:139], v[100:103], off
	s_nop 1
	v_cvt_pk_bf16_f32 v100, v106, v107
	v_cvt_pk_bf16_f32 v101, v104, v105
	v_cvt_pk_bf16_f32 v102, v98, v99
	v_cvt_pk_bf16_f32 v103, v96, v97
	global_store_dwordx4 v[138:139], v[100:103], off offset:256
	s_nop 1
	v_pk_mul_f32 v[100:101], v[178:179], v[212:213]
	v_pk_mul_f32 v[102:103], v[180:181], v[214:215]
	v_pk_fma_f32 v[142:143], v[128:129], v[210:211], v[100:101] neg_lo:[0,0,1] neg_hi:[0,0,1]
	v_pk_mul_f32 v[100:101], v[180:181], v[208:209]
	v_pk_fma_f32 v[138:139], v[132:133], v[208:209], v[102:103] neg_lo:[0,0,1] neg_hi:[0,0,1]
	v_pk_mul_f32 v[102:103], v[178:179], v[210:211]
	v_pk_fma_f32 v[196:197], v[132:133], v[214:215], v[100:101]
	v_pk_fma_f32 v[194:195], v[128:129], v[212:213], v[102:103]
	v_pk_mul_f32 v[100:101], v[90:91], v[196:197]
	v_pk_mul_f32 v[90:91], v[90:91], v[138:139]
	v_pk_mul_f32 v[102:103], v[88:89], v[194:195]
	v_pk_mul_f32 v[88:89], v[88:89], v[142:143]
	v_pk_fma_f32 v[90:91], v[94:95], v[196:197], v[90:91]
	v_pk_fma_f32 v[102:103], v[92:93], v[142:143], v[102:103] neg_lo:[0,0,1] neg_hi:[0,0,1]
	v_pk_fma_f32 v[88:89], v[92:93], v[194:195], v[88:89]
	v_pk_mul_f32 v[92:93], v[174:175], v[90:91] op_sel_hi:[0,1]
	v_pk_mul_f32 v[90:91], v[80:81], v[194:195]
	v_pk_mul_f32 v[80:81], v[80:81], v[142:143]
	v_pk_fma_f32 v[100:101], v[94:95], v[138:139], v[100:101] neg_lo:[0,0,1] neg_hi:[0,0,1]
	v_pk_mul_f32 v[94:95], v[174:175], v[88:89] op_sel_hi:[0,1]
	v_pk_mul_f32 v[88:89], v[82:83], v[196:197]
	v_pk_fma_f32 v[90:91], v[84:85], v[142:143], v[90:91] neg_lo:[0,0,1] neg_hi:[0,0,1]
	v_pk_mul_f32 v[82:83], v[82:83], v[138:139]
	v_pk_fma_f32 v[84:85], v[84:85], v[194:195], v[80:81]
	v_pk_fma_f32 v[80:81], v[86:87], v[196:197], v[82:83]
	v_pk_mul_f32 v[82:83], v[174:175], v[84:85] op_sel_hi:[0,1]
	v_add_u32_e32 v84, 32, v193
	v_and_b32_e32 v85, 0x7ff, v84
	v_pk_fma_f32 v[88:89], v[86:87], v[138:139], v[88:89] neg_lo:[0,0,1] neg_hi:[0,0,1]
	v_lshlrev_b32_e32 v86, s51, v84
	v_lshrrev_b32_e32 v85, s27, v85
	v_and_b32_e32 v86, 0x7ff, v86
	v_and_or_b32 v85, v84, s73, v85
	v_add_u32_e32 v85, v85, v86
	v_cndmask_b32_e32 v84, v85, v84, vcc
	v_pk_mul_f32 v[100:101], v[174:175], v[100:101] op_sel_hi:[0,1]
	v_pk_mul_f32 v[102:103], v[174:175], v[102:103] op_sel_hi:[0,1]
	v_mad_i64_i32 v[84:85], s[52:53], s50, v84, 0
	v_pk_mul_f32 v[88:89], v[174:175], v[88:89] op_sel_hi:[0,1]
	v_pk_mul_f32 v[90:91], v[174:175], v[90:91] op_sel_hi:[0,1]
	v_pk_mul_f32 v[80:81], v[174:175], v[80:81] op_sel_hi:[0,1]
	v_lshl_add_u64 v[198:199], v[84:85], 1, v[176:177]
	v_cvt_pk_bf16_f32 v84, v102, v103
	v_cvt_pk_bf16_f32 v85, v100, v101
	v_cvt_pk_bf16_f32 v86, v94, v95
	v_cvt_pk_bf16_f32 v87, v92, v93
	global_store_dwordx4 v[198:199], v[84:87], off
	s_nop 1
	v_cvt_pk_bf16_f32 v84, v90, v91
	v_cvt_pk_bf16_f32 v85, v88, v89
	v_cvt_pk_bf16_f32 v86, v82, v83
	v_cvt_pk_bf16_f32 v87, v80, v81
	global_store_dwordx4 v[198:199], v[84:87], off offset:256
	s_nop 1
	v_pk_mul_f32 v[84:85], v[178:179], v[194:195]
	v_pk_mul_f32 v[86:87], v[180:181], v[196:197]
	v_pk_fma_f32 v[200:201], v[128:129], v[142:143], v[84:85] neg_lo:[0,0,1] neg_hi:[0,0,1]
	v_pk_mul_f32 v[84:85], v[180:181], v[138:139]
	v_pk_fma_f32 v[198:199], v[132:133], v[138:139], v[86:87] neg_lo:[0,0,1] neg_hi:[0,0,1]
	v_pk_mul_f32 v[86:87], v[178:179], v[142:143]
	v_pk_fma_f32 v[142:143], v[132:133], v[196:197], v[84:85]
	v_pk_fma_f32 v[138:139], v[128:129], v[194:195], v[86:87]
	v_pk_mul_f32 v[84:85], v[74:75], v[142:143]
	v_pk_mul_f32 v[74:75], v[74:75], v[198:199]
	v_pk_mul_f32 v[86:87], v[72:73], v[138:139]
	v_pk_mul_f32 v[72:73], v[72:73], v[200:201]
	v_pk_fma_f32 v[74:75], v[78:79], v[142:143], v[74:75]
	v_pk_fma_f32 v[86:87], v[76:77], v[200:201], v[86:87] neg_lo:[0,0,1] neg_hi:[0,0,1]
	v_pk_fma_f32 v[72:73], v[76:77], v[138:139], v[72:73]
	v_pk_mul_f32 v[76:77], v[174:175], v[74:75] op_sel_hi:[0,1]
	v_pk_mul_f32 v[74:75], v[64:65], v[138:139]
	v_pk_mul_f32 v[64:65], v[64:65], v[200:201]
	v_pk_fma_f32 v[84:85], v[78:79], v[198:199], v[84:85] neg_lo:[0,0,1] neg_hi:[0,0,1]
	v_pk_mul_f32 v[78:79], v[174:175], v[72:73] op_sel_hi:[0,1]
	v_pk_mul_f32 v[72:73], v[66:67], v[142:143]
	v_pk_fma_f32 v[74:75], v[68:69], v[200:201], v[74:75] neg_lo:[0,0,1] neg_hi:[0,0,1]
	v_pk_mul_f32 v[66:67], v[66:67], v[198:199]
	v_pk_fma_f32 v[68:69], v[68:69], v[138:139], v[64:65]
	v_pk_fma_f32 v[64:65], v[70:71], v[142:143], v[66:67]
	v_pk_mul_f32 v[66:67], v[174:175], v[68:69] op_sel_hi:[0,1]
	v_add_u32_e32 v68, 48, v193
	v_and_b32_e32 v69, 0x7ff, v68
	v_pk_fma_f32 v[72:73], v[70:71], v[198:199], v[72:73] neg_lo:[0,0,1] neg_hi:[0,0,1]
	v_lshlrev_b32_e32 v70, s51, v68
	v_lshrrev_b32_e32 v69, s27, v69
	v_and_b32_e32 v70, 0x7ff, v70
	v_and_or_b32 v69, v68, s73, v69
	v_add_u32_e32 v69, v69, v70
	v_cndmask_b32_e32 v68, v69, v68, vcc
	v_pk_mul_f32 v[84:85], v[174:175], v[84:85] op_sel_hi:[0,1]
	v_pk_mul_f32 v[86:87], v[174:175], v[86:87] op_sel_hi:[0,1]
	v_mad_i64_i32 v[68:69], s[52:53], s50, v68, 0
	v_pk_mul_f32 v[72:73], v[174:175], v[72:73] op_sel_hi:[0,1]
	v_pk_mul_f32 v[74:75], v[174:175], v[74:75] op_sel_hi:[0,1]
	v_pk_mul_f32 v[64:65], v[174:175], v[64:65] op_sel_hi:[0,1]
	v_lshl_add_u64 v[138:139], v[68:69], 1, v[176:177]
	v_cvt_pk_bf16_f32 v68, v86, v87
	v_cvt_pk_bf16_f32 v69, v84, v85
	v_cvt_pk_bf16_f32 v70, v78, v79
	v_cvt_pk_bf16_f32 v71, v76, v77
	global_store_dwordx4 v[138:139], v[68:71], off
	s_nop 1
	v_cvt_pk_bf16_f32 v68, v74, v75
	v_cvt_pk_bf16_f32 v69, v72, v73
	v_cvt_pk_bf16_f32 v70, v66, v67
	v_cvt_pk_bf16_f32 v71, v64, v65
	global_store_dwordx4 v[138:139], v[68:71], off offset:256
	v_mov_b32_e32 v138, v149
	v_mov_b32_e32 v139, v151
	v_mov_b32_e32 v68, v145
	v_mov_b32_e32 v69, v147
	v_pk_mul_f32 v[70:71], v[184:185], v[68:69]
	v_mov_b32_e32 v145, v146
	v_pk_mul_f32 v[142:143], v[182:183], v[138:139]
	v_mov_b32_e32 v149, v150
	v_pk_fma_f32 v[146:147], v[140:141], v[144:145], v[70:71] neg_lo:[0,0,1] neg_hi:[0,0,1]
	v_pk_mul_f32 v[70:71], v[136:137], v[138:139]
	v_pk_fma_f32 v[142:143], v[136:137], v[148:149], v[142:143] neg_lo:[0,0,1] neg_hi:[0,0,1]
	v_pk_mul_f32 v[68:69], v[140:141], v[68:69]
	v_pk_fma_f32 v[138:139], v[182:183], v[148:149], v[70:71]
	v_pk_fma_f32 v[136:137], v[184:185], v[144:145], v[68:69]
	v_pk_mul_f32 v[68:69], v[58:59], v[138:139]
	v_pk_mul_f32 v[58:59], v[58:59], v[142:143]
	v_pk_mul_f32 v[70:71], v[56:57], v[136:137]
	v_pk_mul_f32 v[56:57], v[56:57], v[146:147]
	v_pk_fma_f32 v[58:59], v[62:63], v[138:139], v[58:59]
	v_pk_fma_f32 v[70:71], v[60:61], v[146:147], v[70:71] neg_lo:[0,0,1] neg_hi:[0,0,1]
	v_pk_fma_f32 v[56:57], v[60:61], v[136:137], v[56:57]
	v_pk_mul_f32 v[60:61], v[174:175], v[58:59] op_sel_hi:[0,1]
	v_pk_mul_f32 v[58:59], v[48:49], v[136:137]
	v_pk_mul_f32 v[48:49], v[48:49], v[146:147]
	v_add_u32_e32 v140, 0x80, v193
	v_pk_fma_f32 v[68:69], v[62:63], v[142:143], v[68:69] neg_lo:[0,0,1] neg_hi:[0,0,1]
	v_pk_mul_f32 v[62:63], v[174:175], v[56:57] op_sel_hi:[0,1]
	v_pk_mul_f32 v[56:57], v[50:51], v[138:139]
	v_pk_fma_f32 v[58:59], v[52:53], v[146:147], v[58:59] neg_lo:[0,0,1] neg_hi:[0,0,1]
	v_pk_mul_f32 v[50:51], v[50:51], v[142:143]
	v_pk_fma_f32 v[52:53], v[52:53], v[136:137], v[48:49]
	v_pk_fma_f32 v[48:49], v[54:55], v[138:139], v[50:51]
	v_pk_mul_f32 v[50:51], v[174:175], v[52:53] op_sel_hi:[0,1]
	v_and_b32_e32 v52, 0x7ff, v140
	v_lshlrev_b32_e32 v53, s51, v140
	v_lshrrev_b32_e32 v52, s27, v52
	v_and_b32_e32 v53, 0x7ff, v53
	v_and_or_b32 v52, v140, s73, v52
	v_add_u32_e32 v52, v52, v53
	v_cndmask_b32_e32 v52, v52, v140, vcc
	v_pk_mul_f32 v[68:69], v[174:175], v[68:69] op_sel_hi:[0,1]
	v_pk_mul_f32 v[70:71], v[174:175], v[70:71] op_sel_hi:[0,1]
	v_pk_fma_f32 v[56:57], v[54:55], v[142:143], v[56:57] neg_lo:[0,0,1] neg_hi:[0,0,1]
	v_mad_i64_i32 v[52:53], s[52:53], s50, v52, 0
	v_pk_mul_f32 v[56:57], v[174:175], v[56:57] op_sel_hi:[0,1]
	v_pk_mul_f32 v[58:59], v[174:175], v[58:59] op_sel_hi:[0,1]
	v_pk_mul_f32 v[48:49], v[174:175], v[48:49] op_sel_hi:[0,1]
	v_lshl_add_u64 v[140:141], v[52:53], 1, v[176:177]
	v_cvt_pk_bf16_f32 v52, v70, v71
	v_cvt_pk_bf16_f32 v53, v68, v69
	v_cvt_pk_bf16_f32 v54, v62, v63
	v_cvt_pk_bf16_f32 v55, v60, v61
	global_store_dwordx4 v[140:141], v[52:55], off
	s_nop 1
	v_cvt_pk_bf16_f32 v52, v58, v59
	v_cvt_pk_bf16_f32 v53, v56, v57
	v_cvt_pk_bf16_f32 v54, v50, v51
	v_cvt_pk_bf16_f32 v55, v48, v49
	global_store_dwordx4 v[140:141], v[52:55], off offset:256
	s_nop 1
	v_pk_mul_f32 v[52:53], v[178:179], v[136:137]
	v_pk_mul_f32 v[54:55], v[180:181], v[138:139]
	v_pk_fma_f32 v[144:145], v[128:129], v[146:147], v[52:53] neg_lo:[0,0,1] neg_hi:[0,0,1]
	v_pk_mul_f32 v[52:53], v[180:181], v[142:143]
	v_pk_fma_f32 v[140:141], v[132:133], v[142:143], v[54:55] neg_lo:[0,0,1] neg_hi:[0,0,1]
	v_pk_mul_f32 v[54:55], v[178:179], v[146:147]
	v_pk_fma_f32 v[138:139], v[132:133], v[138:139], v[52:53]
	v_pk_fma_f32 v[136:137], v[128:129], v[136:137], v[54:55]
	v_pk_mul_f32 v[52:53], v[42:43], v[138:139]
	v_pk_mul_f32 v[42:43], v[42:43], v[140:141]
	v_pk_mul_f32 v[54:55], v[40:41], v[136:137]
	v_pk_mul_f32 v[40:41], v[40:41], v[144:145]
	v_pk_fma_f32 v[42:43], v[46:47], v[138:139], v[42:43]
	v_pk_fma_f32 v[54:55], v[44:45], v[144:145], v[54:55] neg_lo:[0,0,1] neg_hi:[0,0,1]
	v_pk_fma_f32 v[40:41], v[44:45], v[136:137], v[40:41]
	v_pk_mul_f32 v[44:45], v[174:175], v[42:43] op_sel_hi:[0,1]
	v_pk_mul_f32 v[42:43], v[32:33], v[136:137]
	v_pk_mul_f32 v[32:33], v[32:33], v[144:145]
	v_pk_fma_f32 v[52:53], v[46:47], v[140:141], v[52:53] neg_lo:[0,0,1] neg_hi:[0,0,1]
	v_pk_mul_f32 v[46:47], v[174:175], v[40:41] op_sel_hi:[0,1]
	v_pk_mul_f32 v[40:41], v[34:35], v[138:139]
	v_pk_fma_f32 v[42:43], v[36:37], v[144:145], v[42:43] neg_lo:[0,0,1] neg_hi:[0,0,1]
	v_pk_mul_f32 v[34:35], v[34:35], v[140:141]
	v_pk_fma_f32 v[36:37], v[36:37], v[136:137], v[32:33]
	v_pk_fma_f32 v[32:33], v[38:39], v[138:139], v[34:35]
	v_pk_mul_f32 v[34:35], v[174:175], v[36:37] op_sel_hi:[0,1]
	v_add_u32_e32 v36, 0x90, v193
	v_and_b32_e32 v37, 0x7ff, v36
	v_pk_fma_f32 v[40:41], v[38:39], v[140:141], v[40:41] neg_lo:[0,0,1] neg_hi:[0,0,1]
	v_lshlrev_b32_e32 v38, s51, v36
	v_lshrrev_b32_e32 v37, s27, v37
	v_and_b32_e32 v38, 0x7ff, v38
	v_and_or_b32 v37, v36, s73, v37
	v_add_u32_e32 v37, v37, v38
	v_cndmask_b32_e32 v36, v37, v36, vcc
	v_pk_mul_f32 v[52:53], v[174:175], v[52:53] op_sel_hi:[0,1]
	v_pk_mul_f32 v[54:55], v[174:175], v[54:55] op_sel_hi:[0,1]
	v_mad_i64_i32 v[36:37], s[52:53], s50, v36, 0
	v_pk_mul_f32 v[40:41], v[174:175], v[40:41] op_sel_hi:[0,1]
	v_pk_mul_f32 v[42:43], v[174:175], v[42:43] op_sel_hi:[0,1]
	v_pk_mul_f32 v[32:33], v[174:175], v[32:33] op_sel_hi:[0,1]
	v_lshl_add_u64 v[142:143], v[36:37], 1, v[176:177]
	v_cvt_pk_bf16_f32 v36, v54, v55
	v_cvt_pk_bf16_f32 v37, v52, v53
	v_cvt_pk_bf16_f32 v38, v46, v47
	v_cvt_pk_bf16_f32 v39, v44, v45
	global_store_dwordx4 v[142:143], v[36:39], off
	s_nop 1
	v_cvt_pk_bf16_f32 v36, v42, v43
	v_cvt_pk_bf16_f32 v37, v40, v41
	v_cvt_pk_bf16_f32 v38, v34, v35
	v_cvt_pk_bf16_f32 v39, v32, v33
	global_store_dwordx4 v[142:143], v[36:39], off offset:256
	s_nop 1
	v_pk_mul_f32 v[36:37], v[178:179], v[136:137]
	v_pk_mul_f32 v[38:39], v[180:181], v[138:139]
	v_pk_fma_f32 v[146:147], v[128:129], v[144:145], v[36:37] neg_lo:[0,0,1] neg_hi:[0,0,1]
	v_pk_mul_f32 v[36:37], v[180:181], v[140:141]
	v_pk_fma_f32 v[142:143], v[132:133], v[140:141], v[38:39] neg_lo:[0,0,1] neg_hi:[0,0,1]
	v_pk_mul_f32 v[38:39], v[178:179], v[144:145]
	v_pk_fma_f32 v[138:139], v[132:133], v[138:139], v[36:37]
	v_pk_fma_f32 v[136:137], v[128:129], v[136:137], v[38:39]
	v_pk_mul_f32 v[36:37], v[26:27], v[138:139]
	v_pk_mul_f32 v[26:27], v[26:27], v[142:143]
	v_pk_mul_f32 v[38:39], v[24:25], v[136:137]
	v_pk_mul_f32 v[24:25], v[24:25], v[146:147]
	v_pk_fma_f32 v[26:27], v[30:31], v[138:139], v[26:27]
	v_pk_fma_f32 v[38:39], v[28:29], v[146:147], v[38:39] neg_lo:[0,0,1] neg_hi:[0,0,1]
	v_pk_fma_f32 v[24:25], v[28:29], v[136:137], v[24:25]
	v_pk_mul_f32 v[28:29], v[174:175], v[26:27] op_sel_hi:[0,1]
	v_pk_mul_f32 v[26:27], v[16:17], v[136:137]
	v_pk_mul_f32 v[16:17], v[16:17], v[146:147]
	v_pk_fma_f32 v[36:37], v[30:31], v[142:143], v[36:37] neg_lo:[0,0,1] neg_hi:[0,0,1]
	v_pk_mul_f32 v[30:31], v[174:175], v[24:25] op_sel_hi:[0,1]
	v_pk_mul_f32 v[24:25], v[18:19], v[138:139]
	v_pk_fma_f32 v[26:27], v[20:21], v[146:147], v[26:27] neg_lo:[0,0,1] neg_hi:[0,0,1]
	v_pk_mul_f32 v[18:19], v[18:19], v[142:143]
	v_pk_fma_f32 v[20:21], v[20:21], v[136:137], v[16:17]
	v_pk_fma_f32 v[16:17], v[22:23], v[138:139], v[18:19]
	v_pk_mul_f32 v[18:19], v[174:175], v[20:21] op_sel_hi:[0,1]
	v_add_u32_e32 v20, 0xa0, v193
	v_and_b32_e32 v21, 0x7ff, v20
	v_pk_fma_f32 v[24:25], v[22:23], v[142:143], v[24:25] neg_lo:[0,0,1] neg_hi:[0,0,1]
	v_lshlrev_b32_e32 v22, s51, v20
	v_lshrrev_b32_e32 v21, s27, v21
	v_and_b32_e32 v22, 0x7ff, v22
	v_and_or_b32 v21, v20, s73, v21
	v_add_u32_e32 v21, v21, v22
	v_cndmask_b32_e32 v20, v21, v20, vcc
	v_pk_mul_f32 v[36:37], v[174:175], v[36:37] op_sel_hi:[0,1]
	v_pk_mul_f32 v[38:39], v[174:175], v[38:39] op_sel_hi:[0,1]
	v_mad_i64_i32 v[20:21], s[52:53], s50, v20, 0
	v_pk_mul_f32 v[24:25], v[174:175], v[24:25] op_sel_hi:[0,1]
	v_pk_mul_f32 v[26:27], v[174:175], v[26:27] op_sel_hi:[0,1]
	v_pk_mul_f32 v[16:17], v[174:175], v[16:17] op_sel_hi:[0,1]
	v_lshl_add_u64 v[140:141], v[20:21], 1, v[176:177]
	v_cvt_pk_bf16_f32 v20, v38, v39
	v_cvt_pk_bf16_f32 v21, v36, v37
	v_cvt_pk_bf16_f32 v22, v30, v31
	v_cvt_pk_bf16_f32 v23, v28, v29
	global_store_dwordx4 v[140:141], v[20:23], off
	s_nop 1
	v_cvt_pk_bf16_f32 v20, v26, v27
	v_cvt_pk_bf16_f32 v21, v24, v25
	v_cvt_pk_bf16_f32 v22, v18, v19
	v_cvt_pk_bf16_f32 v23, v16, v17
	global_store_dwordx4 v[140:141], v[20:23], off offset:256
	s_nop 1
	v_pk_mul_f32 v[20:21], v[178:179], v[136:137]
	v_pk_mul_f32 v[22:23], v[180:181], v[138:139]
	v_pk_fma_f32 v[144:145], v[128:129], v[146:147], v[20:21] neg_lo:[0,0,1] neg_hi:[0,0,1]
	v_pk_mul_f32 v[20:21], v[180:181], v[142:143]
	v_pk_fma_f32 v[140:141], v[132:133], v[142:143], v[22:23] neg_lo:[0,0,1] neg_hi:[0,0,1]
	v_pk_mul_f32 v[22:23], v[178:179], v[146:147]
	v_pk_fma_f32 v[132:133], v[132:133], v[138:139], v[20:21]
	v_pk_fma_f32 v[128:129], v[128:129], v[136:137], v[22:23]
	v_pk_mul_f32 v[20:21], v[10:11], v[132:133]
	v_pk_mul_f32 v[10:11], v[10:11], v[140:141]
	v_pk_mul_f32 v[22:23], v[8:9], v[128:129]
	v_pk_mul_f32 v[8:9], v[8:9], v[144:145]
	v_pk_fma_f32 v[10:11], v[14:15], v[132:133], v[10:11]
	v_pk_fma_f32 v[22:23], v[12:13], v[144:145], v[22:23] neg_lo:[0,0,1] neg_hi:[0,0,1]
	v_pk_fma_f32 v[8:9], v[12:13], v[128:129], v[8:9]
	v_pk_mul_f32 v[12:13], v[174:175], v[10:11] op_sel_hi:[0,1]
	v_pk_mul_f32 v[10:11], v[0:1], v[128:129]
	v_pk_mul_f32 v[0:1], v[0:1], v[144:145]
	v_pk_fma_f32 v[20:21], v[14:15], v[140:141], v[20:21] neg_lo:[0,0,1] neg_hi:[0,0,1]
	v_pk_mul_f32 v[14:15], v[174:175], v[8:9] op_sel_hi:[0,1]
	v_pk_mul_f32 v[8:9], v[2:3], v[132:133]
	v_pk_fma_f32 v[10:11], v[4:5], v[144:145], v[10:11] neg_lo:[0,0,1] neg_hi:[0,0,1]
	v_pk_mul_f32 v[2:3], v[2:3], v[140:141]
	v_pk_fma_f32 v[4:5], v[4:5], v[128:129], v[0:1]
	v_pk_fma_f32 v[0:1], v[6:7], v[132:133], v[2:3]
	v_pk_mul_f32 v[2:3], v[174:175], v[4:5] op_sel_hi:[0,1]
	v_add_u32_e32 v4, 0xb0, v193
	v_and_b32_e32 v5, 0x7ff, v4
	v_pk_fma_f32 v[8:9], v[6:7], v[140:141], v[8:9] neg_lo:[0,0,1] neg_hi:[0,0,1]
	v_lshlrev_b32_e32 v6, s51, v4
	v_lshrrev_b32_e32 v5, s27, v5
	v_and_b32_e32 v6, 0x7ff, v6
	v_and_or_b32 v5, v4, s73, v5
	v_add_u32_e32 v5, v5, v6
	v_cndmask_b32_e32 v4, v5, v4, vcc
	v_pk_mul_f32 v[20:21], v[174:175], v[20:21] op_sel_hi:[0,1]
	v_pk_mul_f32 v[22:23], v[174:175], v[22:23] op_sel_hi:[0,1]
	v_mad_i64_i32 v[4:5], s[50:51], s50, v4, 0
	v_pk_mul_f32 v[8:9], v[174:175], v[8:9] op_sel_hi:[0,1]
	v_pk_mul_f32 v[10:11], v[174:175], v[10:11] op_sel_hi:[0,1]
	v_pk_mul_f32 v[0:1], v[174:175], v[0:1] op_sel_hi:[0,1]
	v_lshl_add_u64 v[128:129], v[4:5], 1, v[176:177]
	v_cvt_pk_bf16_f32 v4, v22, v23
	v_cvt_pk_bf16_f32 v5, v20, v21
	v_cvt_pk_bf16_f32 v6, v14, v15
	v_cvt_pk_bf16_f32 v7, v12, v13
	global_store_dwordx4 v[128:129], v[4:7], off
	s_andn2_b64 vcc, exec, s[48:49]
	s_nop 0
	v_cvt_pk_bf16_f32 v4, v10, v11
	v_cvt_pk_bf16_f32 v5, v8, v9
	v_cvt_pk_bf16_f32 v6, v2, v3
	v_cvt_pk_bf16_f32 v7, v0, v1
	global_store_dwordx4 v[128:129], v[4:7], off offset:256
	s_cbranch_vccnz .LBB0_190
	s_nop 0
	v_pk_add_f32 v[4:5], v[124:125], 0 op_sel_hi:[1,0]
	v_pk_add_f32 v[6:7], v[126:127], 0 op_sel_hi:[1,0]
	v_pk_add_f32 v[4:5], v[4:5], v[130:131]
	v_pk_add_f32 v[6:7], v[6:7], v[134:135]
	v_pk_add_f32 v[4:5], v[4:5], v[100:101]
	v_pk_add_f32 v[6:7], v[6:7], v[102:103]
	v_pk_add_f32 v[4:5], v[4:5], v[84:85]
	v_pk_add_f32 v[6:7], v[6:7], v[86:87]
	v_pk_add_f32 v[4:5], v[68:69], v[4:5]
	v_pk_add_f32 v[6:7], v[70:71], v[6:7]
	v_pk_add_f32 v[4:5], v[52:53], v[4:5]
	v_pk_add_f32 v[6:7], v[54:55], v[6:7]
	v_pk_add_f32 v[4:5], v[36:37], v[4:5]
	v_pk_add_f32 v[6:7], v[38:39], v[6:7]
	v_pk_add_f32 v[4:5], v[4:5], v[20:21]
	v_and_b32_e32 v21, 64, v192
	v_xor_b32_e32 v20, 1, v192
	v_add_u32_e32 v39, 64, v21
	v_cmp_lt_i32_e32 vcc, v20, v39
	v_pk_add_f32 v[6:7], v[6:7], v[22:23]
	v_xor_b32_e32 v52, 8, v192
	v_cndmask_b32_e32 v20, v192, v20, vcc
	v_lshlrev_b32_e32 v38, 2, v20
	v_xor_b32_e32 v20, 2, v192
	v_cmp_lt_i32_e32 vcc, v20, v39
	ds_bpermute_b32 v21, v38, v7
	ds_bpermute_b32 v22, v38, v4
	v_cndmask_b32_e32 v20, v192, v20, vcc
	v_lshlrev_b32_e32 v37, 2, v20
	v_xor_b32_e32 v20, 4, v192
	v_cmp_lt_i32_e32 vcc, v20, v39
	ds_bpermute_b32 v23, v38, v5
	s_ashr_i32 s27, s26, 31
	v_cndmask_b32_e32 v20, v192, v20, vcc
	v_lshlrev_b32_e32 v36, 2, v20
	ds_bpermute_b32 v20, v38, v6
	s_waitcnt lgkmcnt(1)
	v_pk_add_f32 v[4:5], v[4:5], v[22:23]
	ds_bpermute_b32 v22, v37, v4
	ds_bpermute_b32 v23, v37, v5
	v_cmp_lt_i32_e32 vcc, v52, v39
	s_waitcnt lgkmcnt(2)
	v_pk_add_f32 v[6:7], v[6:7], v[20:21]
	ds_bpermute_b32 v20, v37, v6
	ds_bpermute_b32 v21, v37, v7
	s_waitcnt lgkmcnt(2)
	v_pk_add_f32 v[22:23], v[4:5], v[22:23]
	ds_bpermute_b32 v54, v36, v22
	ds_bpermute_b32 v55, v36, v23
	v_cndmask_b32_e32 v39, v192, v52, vcc
	s_waitcnt lgkmcnt(2)
	v_pk_add_f32 v[6:7], v[6:7], v[20:21]
	ds_bpermute_b32 v20, v36, v6
	ds_bpermute_b32 v21, v36, v7
	v_lshlrev_b32_e32 v52, 2, v39
	s_add_i32 s48, s81, 0xfffffc00
	s_lshl_b64 s[26:27], s[26:27], 13
	s_ashr_i32 s49, s48, 31
	s_waitcnt lgkmcnt(0)
	v_pk_add_f32 v[4:5], v[6:7], v[20:21]
	v_pk_add_f32 v[20:21], v[22:23], v[54:55]
	ds_bpermute_b32 v6, v52, v4
	ds_bpermute_b32 v7, v52, v5
	ds_bpermute_b32 v22, v52, v20
	ds_bpermute_b32 v23, v52, v21
	v_lshlrev_b32_e32 v39, 2, v162
	s_and_saveexec_b64 s[50:51], s[0:1]
	s_cbranch_execz .LBB0_183
	s_add_u32 s54, s68, s26
	s_addc_u32 s55, s69, s27
	s_lshl_b64 s[52:53], s[48:49], 2
	s_add_u32 s52, s54, s52
	s_addc_u32 s53, s55, s53
	s_lshl_b32 s54, s65, 2
	s_add_u32 s52, s52, s54
	s_waitcnt lgkmcnt(0)
	v_pk_add_f32 v[22:23], v[20:21], v[22:23]
	v_pk_add_f32 v[20:21], v[4:5], v[6:7]
	s_addc_u32 s53, s53, 0
	global_store_dwordx4 v39, v[20:23], s[52:53]
